# a7 + diff attention: running shift m folded into the QK accumulator init (C = -m registers), 32 subtractions per tile removed, exps in place, P packed before V fetch
# speedup vs baseline: 1.0408x; 1.0001x over previous
; DI int tid_l() { int t = threadIdx.x; asm volatile("" : "+v"(t)); return t; }
; #define A_GLOAD(KR, VR, CR, JT) { const int s1_ = (JT) * 64; KR = *(const u32x4*)(kp + (size_t)s1_ * ldk); \
;     _Pragma("unroll") for (int i_ = 0; i_ < DVT / 2; ++i_) VR[i_] = *(const u32x4*)(vp + (size_t)(64 * i_) * SEQ + s1_); \
;     if (FOX) { if (tid < 16) { f32x4 t_ = *(const f32x4*)(cbase + s1_ + tid * 4); CR[0] = -t_[0]; CR[1] = -t_[1]; CR[2] = -t_[2]; CR[3] = -t_[3]; } } }
; template <int DVT, bool FOX> ...
;     ...
;   const int tid = tid_l(), lane = tid & 63;
;   const int r = lane & 31, hh = lane >> 5;
;   const int lrow = tid >> 3, lch = tid & 7;
;   bf16x8 qf[4];
; #pragma unroll
;   for (int ks = 0; ks < 4; ++ks) qf[ks] = *(const bf16x8*)(qrow + ks * 16 + hh * 8);
; #pragma unroll
;   for (int d = 0; d < DVT; ++d)
; #pragma unroll
;     for (int i = 0; i < 16; ++i) o[d][i] = 0.f;
;   float m = 0.f, l = 0.f;
;   u32x4 kr0, kr1, vr0[DVT / 2], vr1[DVT / 2]; f32x4 cr0 = {0.f, 0.f, 0.f, 0.f}, cr1 = {0.f, 0.f, 0.f, 0.f};
;   const bf16_t* kp = kbase + (size_t)lrow * ldk + lch * 8;
;   const bf16_t* vp = vtbase + (size_t)lrow * SEQ + lch * 8;
;     ...
;   int j = j_hi;
;   A_GLOAD(kr0, vr0, cr0, j);
;   if (j >= 1) A_GLOAD(kr1, vr1, cr1, j - 1);
; DI void diff_phase(const Params& p, const int j_even, char* lds) {
;     ...
;       const int qb = half == 0 ? 63 - pp : pp;
;       const int t0 = qb * 256, tq0 = t0 + wave * 32, tq = tq0 + r;
;       const int nkv = (t0 + 256) >> 6, my_last = tq0 >> 6;
;       f32x16 o1[4], o2[4]; float l1, l2;
;       attn_pass<4, false>(bq + (size_t)(b * SEQ + tq) * 512 + h * 128, bk + (size_t)(b * SEQ) * 512 + h * 128, 512,
;                           bvT + (size_t)(bh * 128) * SEQ, nullptr, nkv - 1, my_last, 0, tq, 0.f, o1, l1, lds);
.LBB0_636:
	s_and_b64 s[2:3], s[12:13], exec
	v_readlane_b32 s2, v254, 3
	v_readlane_b32 s3, v254, 4
	s_cselect_b32 s2, s3, s2
	s_lshl_b32 s3, s2, 8
	s_add_i32 s2, s3, s24
	v_add_u32_e32 v160, s2, v179
	v_ashrrev_i32_e32 v161, 31, v160
	v_mov_b32_e32 v5, v192
	v_lshlrev_b64 v[2:3], 10, v[160:161]
	v_lshl_add_u64 v[162:163], s[6:7], 0, v[2:3]
	v_bfe_u32 v4, v5, 5, 1
	v_ashrrev_i32_e32 v2, 3, v5
	v_lshlrev_b32_e32 v0, 4, v4
	v_lshl_add_u64 v[6:7], v[162:163], 0, v[0:1]
	v_ashrrev_i32_e32 v3, 31, v2
	global_load_dwordx4 v[112:115], v[6:7], off
	global_load_dwordx4 v[116:119], v[6:7], off offset:32
	global_load_dwordx4 v[120:123], v[6:7], off offset:64
	global_load_dwordx4 v[124:127], v[6:7], off offset:96
	v_and_b32_e32 v0, 7, v5
	v_lshlrev_b64 v[6:7], 10, v[2:3]
	v_lshl_add_u64 v[6:7], s[8:9], 0, v[6:7]
	v_lshlrev_b32_e32 v0, 4, v0
	v_lshl_add_u64 v[164:165], v[6:7], 0, v[0:1]
	v_lshlrev_b64 v[6:7], 15, v[2:3]
	s_or_b32 s4, s3, 0xc0
	v_lshl_add_u64 v[6:7], s[10:11], 0, v[6:7]
	s_ashr_i32 s5, s4, 31
	v_lshl_add_u64 v[166:167], v[6:7], 0, v[0:1]
	v_subrev_u32_e32 v217, s8, v164
	v_subrev_u32_e32 v222, s10, v166
	v_add_u32_e32 v227, 0x200000, v222
	s_lshl_b64 s[16:17], s[4:5], 10
	v_lshl_add_u64 v[6:7], v[164:165], 0, s[16:17]
	v_lshl_add_u64 v[8:9], s[4:5], 1, v[166:167]
	global_load_dwordx4 v[128:131], v[6:7], off
	global_load_dwordx4 v[132:135], v[8:9], off
	v_add_co_u32_e32 v6, vcc, 0x200000, v8
	s_addk_i32 s3, 0x100
	s_nop 0
	v_addc_co_u32_e32 v7, vcc, 0, v9, vcc
	global_load_dwordx4 v[136:139], v[6:7], off
	s_ashr_i32 s3, s3, 6
	s_cmp_gt_i32 s3, 1
	v_mov_b32_e32 v168, 0
	v_mov_b32_e32 v228, 0
	v_mov_b32_e32 v229, 0
	v_mov_b32_e32 v230, 0
	v_mov_b32_e32 v231, 0
	v_mov_b32_e32 v232, 0
	v_mov_b32_e32 v233, 0
	v_mov_b32_e32 v234, 0
	v_mov_b32_e32 v235, 0
	v_mov_b32_e32 v236, 0
	v_mov_b32_e32 v237, 0
	v_mov_b32_e32 v238, 0
	v_mov_b32_e32 v239, 0
	v_mov_b32_e32 v240, 0
	v_mov_b32_e32 v241, 0
	v_mov_b32_e32 v242, 0
	v_mov_b32_e32 v243, 0
	s_cselect_b64 s[18:19], -1, 0
	s_cmp_lt_i32 s3, 2
	v_mov_b32_e32 v144, 0
	v_mov_b32_e32 v145, 0
	v_mov_b32_e32 v146, 0
	v_mov_b32_e32 v147, 0
	v_mov_b32_e32 v148, 0
	v_mov_b32_e32 v149, 0
	v_mov_b32_e32 v150, 0
	v_mov_b32_e32 v151, 0
	s_cbranch_scc1 .LBB0_638
	s_sub_i32 s96, s4, 64
	s_lshl_b64 s[14:15], s[96:97], 10
	v_lshl_add_u64 v[6:7], v[164:165], 0, s[14:15]
	v_lshl_add_u64 v[8:9], s[96:97], 1, v[166:167]
	global_load_dwordx4 v[140:143], v[6:7], off
	global_load_dwordx4 v[144:147], v[8:9], off
	v_add_co_u32_e32 v6, vcc, 0x200000, v8
	s_nop 1
	v_addc_co_u32_e32 v7, vcc, 0, v9, vcc
	global_load_dwordx4 v[148:151], v[6:7], off

; #define MFMA32(a, b, c) __builtin_amdgcn_mfma_f32_32x32x16_bf16((a), (b), (c), 0, 0, 0)
; DI float xmax32(float v) { const u32x2 r_ = __builtin_amdgcn_permlane32_swap(__float_as_uint(v), __float_as_uint(v), false, false); return fmaxf(__uint_as_float(r_[0]), __uint_as_float(r_[1])); }
; template <int DVT, bool FOX>
; DI void attn_step(const char* kb, const bf16x8 (&qf)[4], f32x16 (&o)[DVT], float& m, float& l, const bool diag, const int j, const int tq, const int r, const int hh) {
;     ...
; #pragma unroll
;   for (int ks = 0; ks < 4; ++ks)
; #pragma unroll
;     for (int kt = 0; kt < 2; ++kt) st[kt] = MFMA32(kf[ks * 2 + kt], qf[ks], st[kt]);
;   bf16x8 va[DVT], vn[DVT];
; #pragma unroll
;   for (int d = 0; d < DVT; ++d) va[d] = *(const bf16x8*)(vb + (d * 32 + r) * LROW + (8 * hh) * 2);
;   __builtin_amdgcn_sched_barrier(0);
;   {
;     const f32x2 mm = {m, m};
; #pragma unroll
;     for (int kt = 0; kt < 2; ++kt)
; #pragma unroll
;       for (int i = 0; i < 8; ++i) { f32x2 z = {st[kt][2 * i], st[kt][2 * i + 1]}; z = z - mm; st[kt][2 * i] = z[0]; st[kt][2 * i + 1] = z[1]; }
;   }
;   if (FOX) {
;     if (diag) {
; #pragma unroll
;       for (int kt = 0; kt < 2; ++kt)
; #pragma unroll
;         for (int i = 0; i < 16; ++i) {
;           const int key = j * 64 + kt * 32 + (i & 3) + 8 * (i >> 2) + 4 * hh;
;           if (key > tq) st[kt][i] = -INFINITY;
;         }
;     }
;   }
;   float mx;
;   {
;     float a0 = fmaxf(fmaxf(st[0][0], st[0][1]), st[0][2]), a1 = fmaxf(fmaxf(st[1][0], st[1][1]), st[1][2]);
; #pragma unroll
;     for (int i = 3; i < 15; i += 2) { a0 = fmaxf(fmaxf(a0, st[0][i]), st[0][i + 1]); a1 = fmaxf(fmaxf(a1, st[1][i]), st[1][i + 1]); }
;     mx = fmaxf(fmaxf(a0, a1), fmaxf(st[0][15], st[1][15]));
;   }
;   mx = xmax32(mx);
;   if (__any(diag || mx > 8.f)) {
;     const float d = (diag || mx > 0.f) ? mx : 0.f;
;     const float alpha = diag ? 0.f : __builtin_amdgcn_exp2f(-d);
;     m += d;
;     l *= alpha;
; #pragma unroll
;     for (int dd = 0; dd < DVT; ++dd)
; #pragma unroll
;       for (int i = 0; i < 16; ++i) o[dd][i] *= alpha;
;     const f32x2 d2 = {d, d};
; #pragma unroll
;     for (int kt = 0; kt < 2; ++kt)
; #pragma unroll
;       for (int i = 0; i < 8; ++i) { f32x2 z = {st[kt][2 * i], st[kt][2 * i + 1]}; z = z - d2; st[kt][2 * i] = z[0]; st[kt][2 * i + 1] = z[1]; }
;   }
.LBB0_642:
	s_cmp_gt_i32 s3, s25
	s_cbranch_scc1 .LBB0_646
	ds_read_b128 v[2:5], v184
	ds_read_b128 v[6:9], v184 offset:32
	ds_read_b128 v[10:13], v184 offset:4608
	ds_read_b128 v[152:155], v184 offset:4640
	ds_read_b128 v[170:173], v184 offset:64
	ds_read_b128 v[174:177], v184 offset:96
	ds_read_b128 v[186:189], v184 offset:4672
	ds_read_b128 v[208:211], v184 offset:4704
	s_add_i32 s15, s26, s2
	s_cmp_eq_u32 s15, -1
	s_cselect_b64 s[22:23], -1, 0
	s_waitcnt lgkmcnt(7)
	v_mfma_f32_32x32x16_bf16 v[96:111], v[2:5], v[112:115], v[228:243]
	s_waitcnt lgkmcnt(5)
	v_mfma_f32_32x32x16_bf16 v[80:95], v[10:13], v[112:115], v[228:243]
	v_mfma_f32_32x32x16_bf16 v[96:111], v[6:9], v[116:119], v[96:111]
	s_waitcnt lgkmcnt(4)
	v_mfma_f32_32x32x16_bf16 v[80:95], v[152:155], v[116:119], v[80:95]
	ds_read_b128 v[152:155], v184 offset:9216
	ds_read_b128 v[10:13], v184 offset:13824
	ds_read_b128 v[6:9], v184 offset:18432
	ds_read_b128 v[2:5], v184 offset:23040
	s_waitcnt lgkmcnt(7)
	v_mfma_f32_32x32x16_bf16 v[96:111], v[170:173], v[120:123], v[96:111]
	s_waitcnt lgkmcnt(5)
	v_mfma_f32_32x32x16_bf16 v[80:95], v[186:189], v[120:123], v[80:95]
	v_mfma_f32_32x32x16_bf16 v[96:111], v[174:177], v[124:127], v[96:111]
	s_waitcnt lgkmcnt(4)
	v_mfma_f32_32x32x16_bf16 v[80:95], v[208:211], v[124:127], v[80:95]
	s_nop 10
	v_max3_f32 v224, v96, v97, v98
	v_max3_f32 v225, v80, v81, v82
	v_max3_f32 v224, v224, v99, v100
	v_max3_f32 v225, v225, v83, v84
	v_max3_f32 v224, v224, v101, v102
	v_max3_f32 v225, v225, v85, v86
	v_max3_f32 v224, v224, v103, v104
	v_max3_f32 v225, v225, v87, v88
	v_max3_f32 v224, v224, v105, v106
	v_max3_f32 v225, v225, v89, v90
	v_max3_f32 v224, v224, v107, v108
	v_max3_f32 v225, v225, v91, v92
	v_max3_f32 v224, v224, v109, v110
	v_max3_f32 v225, v225, v93, v94
	v_max_f32_e32 v226, v111, v95
	v_max3_f32 v224, v224, v225, v226
	v_mov_b32_e32 v225, v224
	s_nop 1
	v_permlane32_swap_b32_e32 v224, v225
	v_max_f32_e32 v224, v224, v225
	v_cmp_lt_f32_e32 vcc, s92, v224
	s_or_b64 vcc, s[22:23], vcc
	s_cbranch_vccz .LBB0_645
	v_cmp_lt_f32_e32 vcc, 0, v224
	s_or_b64 vcc, s[22:23], vcc
	s_nop 0
	v_cndmask_b32_e32 v225, 0, v224, vcc
	v_exp_f32_e64 v224, -v225
	v_add_f32_e32 v168, v168, v225
	v_sub_f32_e32 v228, v228, v225
	v_sub_f32_e32 v229, v229, v225
	v_sub_f32_e32 v230, v230, v225
	v_sub_f32_e32 v231, v231, v225
	v_sub_f32_e32 v232, v232, v225
	v_sub_f32_e32 v233, v233, v225
	v_sub_f32_e32 v234, v234, v225
	v_sub_f32_e32 v235, v235, v225
	v_sub_f32_e32 v236, v236, v225
	v_sub_f32_e32 v237, v237, v225
	v_sub_f32_e32 v238, v238, v225
	v_sub_f32_e32 v239, v239, v225
	v_sub_f32_e32 v240, v240, v225
	v_sub_f32_e32 v241, v241, v225
	v_sub_f32_e32 v242, v242, v225
	v_sub_f32_e32 v243, v243, v225
	v_sub_f32_e32 v96, v96, v225
	v_sub_f32_e32 v97, v97, v225
	v_cndmask_b32_e64 v224, v224, 0, s[22:23]
	v_mul_f32_e32 v0, v0, v224
	v_pk_mul_f32 v[78:79], v[78:79], v[224:225] op_sel_hi:[1, 0]
	v_pk_mul_f32 v[76:77], v[76:77], v[224:225] op_sel_hi:[1, 0]
	v_pk_mul_f32 v[74:75], v[74:75], v[224:225] op_sel_hi:[1, 0]
	v_pk_mul_f32 v[72:73], v[72:73], v[224:225] op_sel_hi:[1, 0]
	v_pk_mul_f32 v[70:71], v[70:71], v[224:225] op_sel_hi:[1, 0]
	v_pk_mul_f32 v[68:69], v[68:69], v[224:225] op_sel_hi:[1, 0]
	v_pk_mul_f32 v[66:67], v[66:67], v[224:225] op_sel_hi:[1, 0]
	v_pk_mul_f32 v[64:65], v[64:65], v[224:225] op_sel_hi:[1, 0]
	v_pk_mul_f32 v[62:63], v[62:63], v[224:225] op_sel_hi:[1, 0]
	v_pk_mul_f32 v[60:61], v[60:61], v[224:225] op_sel_hi:[1, 0]
	v_pk_mul_f32 v[58:59], v[58:59], v[224:225] op_sel_hi:[1, 0]
	v_pk_mul_f32 v[56:57], v[56:57], v[224:225] op_sel_hi:[1, 0]
	v_pk_mul_f32 v[54:55], v[54:55], v[224:225] op_sel_hi:[1, 0]
	v_pk_mul_f32 v[52:53], v[52:53], v[224:225] op_sel_hi:[1, 0]
	v_pk_mul_f32 v[50:51], v[50:51], v[224:225] op_sel_hi:[1, 0]
	v_pk_mul_f32 v[48:49], v[48:49], v[224:225] op_sel_hi:[1, 0]
	v_pk_mul_f32 v[46:47], v[46:47], v[224:225] op_sel_hi:[1, 0]
	v_pk_mul_f32 v[44:45], v[44:45], v[224:225] op_sel_hi:[1, 0]
	v_pk_mul_f32 v[42:43], v[42:43], v[224:225] op_sel_hi:[1, 0]
	v_pk_mul_f32 v[40:41], v[40:41], v[224:225] op_sel_hi:[1, 0]
	v_pk_mul_f32 v[38:39], v[38:39], v[224:225] op_sel_hi:[1, 0]
	v_pk_mul_f32 v[36:37], v[36:37], v[224:225] op_sel_hi:[1, 0]
	v_pk_mul_f32 v[34:35], v[34:35], v[224:225] op_sel_hi:[1, 0]
	v_pk_mul_f32 v[32:33], v[32:33], v[224:225] op_sel_hi:[1, 0]
	v_pk_mul_f32 v[30:31], v[30:31], v[224:225] op_sel_hi:[1, 0]
	v_pk_mul_f32 v[28:29], v[28:29], v[224:225] op_sel_hi:[1, 0]
	v_pk_mul_f32 v[26:27], v[26:27], v[224:225] op_sel_hi:[1, 0]
	v_pk_mul_f32 v[24:25], v[24:25], v[224:225] op_sel_hi:[1, 0]
	v_pk_mul_f32 v[22:23], v[22:23], v[224:225] op_sel_hi:[1, 0]
	v_pk_mul_f32 v[20:21], v[20:21], v[224:225] op_sel_hi:[1, 0]
	v_pk_mul_f32 v[18:19], v[18:19], v[224:225] op_sel_hi:[1, 0]
	v_pk_mul_f32 v[16:17], v[16:17], v[224:225] op_sel_hi:[1, 0]
	v_sub_f32_e32 v98, v98, v225
	v_sub_f32_e32 v99, v99, v225
	v_sub_f32_e32 v100, v100, v225
	v_sub_f32_e32 v101, v101, v225
	v_sub_f32_e32 v102, v102, v225
	v_sub_f32_e32 v103, v103, v225
	v_sub_f32_e32 v104, v104, v225
	v_sub_f32_e32 v105, v105, v225
	v_sub_f32_e32 v106, v106, v225
	v_sub_f32_e32 v107, v107, v225
	v_sub_f32_e32 v108, v108, v225
	v_sub_f32_e32 v109, v109, v225
	v_sub_f32_e32 v110, v110, v225
	v_sub_f32_e32 v111, v111, v225
	v_sub_f32_e32 v80, v80, v225
	v_sub_f32_e32 v81, v81, v225
	v_sub_f32_e32 v82, v82, v225
	v_sub_f32_e32 v83, v83, v225
	v_sub_f32_e32 v84, v84, v225
	v_sub_f32_e32 v85, v85, v225
	v_sub_f32_e32 v86, v86, v225
	v_sub_f32_e32 v87, v87, v225
	v_sub_f32_e32 v88, v88, v225
	v_sub_f32_e32 v89, v89, v225
	v_sub_f32_e32 v90, v90, v225
	v_sub_f32_e32 v91, v91, v225
	v_sub_f32_e32 v92, v92, v225
	v_sub_f32_e32 v93, v93, v225
	v_sub_f32_e32 v94, v94, v225
	v_sub_f32_e32 v95, v95, v225
; template <int DVT, bool FOX>
; DI void attn_step(const char* kb, const bf16x8 (&qf)[4], f32x16 (&o)[DVT], float& m, float& l, const bool diag, const int j, const int tq, const int r, const int hh) {
;     ...
;   f32x2 ls2 = {0.f, 0.f};
; #pragma unroll
;   for (int kt = 0; kt < 2; ++kt)
; #pragma unroll
;     for (int i = 0; i < 8; ++i) {
;       f32x2 pv = {__builtin_amdgcn_exp2f(st[kt][2 * i]), __builtin_amdgcn_exp2f(st[kt][2 * i + 1])};
;       st[kt][2 * i] = pv[0]; st[kt][2 * i + 1] = pv[1];
;       ls2 = ls2 + pv;
;     }
;   l += ls2[0] + ls2[1];
;   __builtin_amdgcn_sched_barrier(0);
;     ...
;   A_PVGROUP(0, va, vn); A_PVGROUP(1, vn, va); A_PVGROUP(2, va, vn); A_PVGROUP(3, vn, va);
.LBB0_645:
	v_exp_f32_e32 v96, v96
	v_exp_f32_e32 v97, v97
	v_exp_f32_e32 v98, v98
	v_exp_f32_e32 v99, v99
	v_pk_add_f32 v[224:225], v[96:97], 0 op_sel_hi:[1,0]
	v_exp_f32_e32 v100, v100
	v_exp_f32_e32 v101, v101
	v_pk_add_f32 v[224:225], v[98:99], v[224:225]
	v_exp_f32_e32 v102, v102
	v_exp_f32_e32 v103, v103
	v_pk_add_f32 v[224:225], v[100:101], v[224:225]
	v_exp_f32_e32 v104, v104
	v_exp_f32_e32 v105, v105
	v_pk_add_f32 v[224:225], v[102:103], v[224:225]
	v_exp_f32_e32 v106, v106
	v_exp_f32_e32 v107, v107
	v_pk_add_f32 v[224:225], v[104:105], v[224:225]
	v_exp_f32_e32 v108, v108
	v_exp_f32_e32 v109, v109
	v_pk_add_f32 v[224:225], v[106:107], v[224:225]
	v_exp_f32_e32 v110, v110
	v_exp_f32_e32 v111, v111
	v_pk_add_f32 v[224:225], v[108:109], v[224:225]
	v_exp_f32_e32 v80, v80
	v_exp_f32_e32 v81, v81
	v_pk_add_f32 v[224:225], v[110:111], v[224:225]
	v_exp_f32_e32 v82, v82
	v_exp_f32_e32 v83, v83
	v_pk_add_f32 v[224:225], v[80:81], v[224:225]
	v_exp_f32_e32 v84, v84
	v_exp_f32_e32 v85, v85
	v_pk_add_f32 v[224:225], v[82:83], v[224:225]
	v_exp_f32_e32 v86, v86
	v_exp_f32_e32 v87, v87
	v_pk_add_f32 v[224:225], v[84:85], v[224:225]
	v_exp_f32_e32 v88, v88
	v_exp_f32_e32 v89, v89
	v_pk_add_f32 v[224:225], v[86:87], v[224:225]
	v_exp_f32_e32 v90, v90
	v_exp_f32_e32 v91, v91
	v_pk_add_f32 v[224:225], v[88:89], v[224:225]
	v_exp_f32_e32 v92, v92
	v_exp_f32_e32 v93, v93
	v_pk_add_f32 v[224:225], v[90:91], v[224:225]
	v_exp_f32_e32 v94, v94
	v_exp_f32_e32 v95, v95
	v_pk_add_f32 v[224:225], v[92:93], v[224:225]
	s_nop 0
	v_pk_add_f32 v[224:225], v[94:95], v[224:225]
	v_cvt_pk_bf16_f32 v244, v96, v97
	v_cvt_pk_bf16_f32 v245, v98, v99
	v_cvt_pk_bf16_f32 v246, v100, v101
	v_cvt_pk_bf16_f32 v247, v102, v103
	v_cvt_pk_bf16_f32 v248, v104, v105
	v_cvt_pk_bf16_f32 v249, v106, v107
	v_cvt_pk_bf16_f32 v250, v108, v109
	v_cvt_pk_bf16_f32 v251, v110, v111
	v_cvt_pk_bf16_f32 v212, v80, v81
	v_cvt_pk_bf16_f32 v213, v82, v83
	v_cvt_pk_bf16_f32 v214, v84, v85
	v_cvt_pk_bf16_f32 v215, v86, v87
	v_cvt_pk_bf16_f32 v218, v88, v89
	v_cvt_pk_bf16_f32 v219, v90, v91
	v_cvt_pk_bf16_f32 v220, v92, v93
	v_cvt_pk_bf16_f32 v221, v94, v95
	v_add_f32_e32 v224, v224, v225
	s_nop 0
	v_add_f32_e32 v0, v0, v224
	ds_read_b128 v[80:83], v184 offset:9248
	ds_read_b128 v[84:87], v184 offset:13856
	ds_read_b128 v[88:91], v184 offset:18464
	ds_read_b128 v[92:95], v184 offset:23072
	s_waitcnt lgkmcnt(7)
	v_mfma_f32_32x32x16_bf16 v[64:79], v[152:155], v[244:247], v[64:79]
	s_waitcnt lgkmcnt(6)
	v_mfma_f32_32x32x16_bf16 v[48:63], v[10:13], v[244:247], v[48:63]
	s_waitcnt lgkmcnt(5)
	v_mfma_f32_32x32x16_bf16 v[32:47], v[6:9], v[244:247], v[32:47]
	s_waitcnt lgkmcnt(4)
	v_mfma_f32_32x32x16_bf16 v[16:31], v[2:5], v[244:247], v[16:31]
	ds_read_b128 v[2:5], v184 offset:9280
	ds_read_b128 v[6:9], v184 offset:13888
	ds_read_b128 v[10:13], v184 offset:18496
	ds_read_b128 v[96:99], v184 offset:23104
	s_waitcnt lgkmcnt(7)
	v_mfma_f32_32x32x16_bf16 v[64:79], v[80:83], v[248:251], v[64:79]
	s_waitcnt lgkmcnt(6)
	v_mfma_f32_32x32x16_bf16 v[48:63], v[84:87], v[248:251], v[48:63]
	s_waitcnt lgkmcnt(5)
	v_mfma_f32_32x32x16_bf16 v[32:47], v[88:91], v[248:251], v[32:47]
	s_waitcnt lgkmcnt(4)
	v_mfma_f32_32x32x16_bf16 v[16:31], v[92:95], v[248:251], v[16:31]
	ds_read_b128 v[80:83], v184 offset:9312
	ds_read_b128 v[84:87], v184 offset:13920
	ds_read_b128 v[88:91], v184 offset:18528
	ds_read_b128 v[92:95], v184 offset:23136
	s_waitcnt lgkmcnt(7)
	v_mfma_f32_32x32x16_bf16 v[64:79], v[2:5], v[212:215], v[64:79]
	s_waitcnt lgkmcnt(6)
	v_mfma_f32_32x32x16_bf16 v[48:63], v[6:9], v[212:215], v[48:63]
	s_waitcnt lgkmcnt(5)
	v_mfma_f32_32x32x16_bf16 v[32:47], v[10:13], v[212:215], v[32:47]
	s_waitcnt lgkmcnt(4)
	v_mfma_f32_32x32x16_bf16 v[16:31], v[96:99], v[212:215], v[16:31]
	s_waitcnt lgkmcnt(3)
	v_mfma_f32_32x32x16_bf16 v[64:79], v[80:83], v[218:221], v[64:79]
	s_waitcnt lgkmcnt(2)
	v_mfma_f32_32x32x16_bf16 v[48:63], v[84:87], v[218:221], v[48:63]
	s_waitcnt lgkmcnt(1)
	v_mfma_f32_32x32x16_bf16 v[32:47], v[88:91], v[218:221], v[32:47]
	s_waitcnt lgkmcnt(0)
	v_mfma_f32_32x32x16_bf16 v[16:31], v[92:95], v[218:221], v[16:31]

; #define MFMA32(a, b, c) __builtin_amdgcn_mfma_f32_32x32x16_bf16((a), (b), (c), 0, 0, 0)
; DI float xmax32(float v) { const u32x2 r_ = __builtin_amdgcn_permlane32_swap(__float_as_uint(v), __float_as_uint(v), false, false); return fmaxf(__uint_as_float(r_[0]), __uint_as_float(r_[1])); }
; template <int DVT, bool FOX>
; DI void attn_step(const char* kb, const bf16x8 (&qf)[4], f32x16 (&o)[DVT], float& m, float& l, const bool diag, const int j, const int tq, const int r, const int hh) {
;     ...
; #pragma unroll
;   for (int ks = 0; ks < 4; ++ks)
; #pragma unroll
;     for (int kt = 0; kt < 2; ++kt) st[kt] = MFMA32(kf[ks * 2 + kt], qf[ks], st[kt]);
;   bf16x8 va[DVT], vn[DVT];
; #pragma unroll
;   for (int d = 0; d < DVT; ++d) va[d] = *(const bf16x8*)(vb + (d * 32 + r) * LROW + (8 * hh) * 2);
;   __builtin_amdgcn_sched_barrier(0);
;   {
;     const f32x2 mm = {m, m};
; #pragma unroll
;     for (int kt = 0; kt < 2; ++kt)
; #pragma unroll
;       for (int i = 0; i < 8; ++i) { f32x2 z = {st[kt][2 * i], st[kt][2 * i + 1]}; z = z - mm; st[kt][2 * i] = z[0]; st[kt][2 * i + 1] = z[1]; }
;   }
;   if (FOX) {
;     if (diag) {
; #pragma unroll
;       for (int kt = 0; kt < 2; ++kt)
; #pragma unroll
;         for (int i = 0; i < 16; ++i) {
;           const int key = j * 64 + kt * 32 + (i & 3) + 8 * (i >> 2) + 4 * hh;
;           if (key > tq) st[kt][i] = -INFINITY;
;         }
;     }
;   }
;   float mx;
;   {
;     float a0 = fmaxf(fmaxf(st[0][0], st[0][1]), st[0][2]), a1 = fmaxf(fmaxf(st[1][0], st[1][1]), st[1][2]);
; #pragma unroll
;     for (int i = 3; i < 15; i += 2) { a0 = fmaxf(fmaxf(a0, st[0][i]), st[0][i + 1]); a1 = fmaxf(fmaxf(a1, st[1][i]), st[1][i + 1]); }
;     mx = fmaxf(fmaxf(a0, a1), fmaxf(st[0][15], st[1][15]));
;   }
;   mx = xmax32(mx);
;   if (__any(diag || mx > 8.f)) {
;     const float d = (diag || mx > 0.f) ? mx : 0.f;
;     const float alpha = diag ? 0.f : __builtin_amdgcn_exp2f(-d);
;     m += d;
;     l *= alpha;
; #pragma unroll
;     for (int dd = 0; dd < DVT; ++dd)
; #pragma unroll
;       for (int i = 0; i < 16; ++i) o[dd][i] *= alpha;
;     const f32x2 d2 = {d, d};
; #pragma unroll
;     for (int kt = 0; kt < 2; ++kt)
; #pragma unroll
;       for (int i = 0; i < 8; ++i) { f32x2 z = {st[kt][2 * i], st[kt][2 * i + 1]}; z = z - d2; st[kt][2 * i] = z[0]; st[kt][2 * i + 1] = z[1]; }
;   }
.LBB0_650:
	ds_read_b128 v[2:5], v184 offset:27904
	ds_read_b128 v[6:9], v184 offset:27936
	ds_read_b128 v[10:13], v184 offset:32512
	ds_read_b128 v[152:155], v184 offset:32544
	ds_read_b128 v[170:173], v184 offset:27968
	ds_read_b128 v[174:177], v184 offset:28000
	ds_read_b128 v[186:189], v184 offset:32576
	ds_read_b128 v[208:211], v184 offset:32608
	s_cmp_eq_u32 s25, s2
	s_cselect_b64 s[22:23], -1, 0
	s_waitcnt lgkmcnt(7)
	v_mfma_f32_32x32x16_bf16 v[96:111], v[2:5], v[112:115], v[228:243]
	s_waitcnt lgkmcnt(5)
	v_mfma_f32_32x32x16_bf16 v[80:95], v[10:13], v[112:115], v[228:243]
	v_mfma_f32_32x32x16_bf16 v[96:111], v[6:9], v[116:119], v[96:111]
	s_waitcnt lgkmcnt(4)
	v_mfma_f32_32x32x16_bf16 v[80:95], v[152:155], v[116:119], v[80:95]
	ds_read_b128 v[152:155], v184 offset:37120
	ds_read_b128 v[10:13], v184 offset:41728
	ds_read_b128 v[6:9], v184 offset:46336
	ds_read_b128 v[2:5], v184 offset:50944
	s_waitcnt lgkmcnt(7)
	v_mfma_f32_32x32x16_bf16 v[96:111], v[170:173], v[120:123], v[96:111]
	s_waitcnt lgkmcnt(5)
	v_mfma_f32_32x32x16_bf16 v[80:95], v[186:189], v[120:123], v[80:95]
	v_mfma_f32_32x32x16_bf16 v[96:111], v[174:177], v[124:127], v[96:111]
	s_waitcnt lgkmcnt(4)
	v_mfma_f32_32x32x16_bf16 v[80:95], v[208:211], v[124:127], v[80:95]
	s_nop 10
	v_max3_f32 v224, v96, v97, v98
	v_max3_f32 v225, v80, v81, v82
	v_max3_f32 v224, v224, v99, v100
	v_max3_f32 v225, v225, v83, v84
	v_max3_f32 v224, v224, v101, v102
	v_max3_f32 v225, v225, v85, v86
	v_max3_f32 v224, v224, v103, v104
	v_max3_f32 v225, v225, v87, v88
	v_max3_f32 v224, v224, v105, v106
	v_max3_f32 v225, v225, v89, v90
	v_max3_f32 v224, v224, v107, v108
	v_max3_f32 v225, v225, v91, v92
	v_max3_f32 v224, v224, v109, v110
	v_max3_f32 v225, v225, v93, v94
	v_max_f32_e32 v226, v111, v95
	v_max3_f32 v224, v224, v225, v226
	v_mov_b32_e32 v225, v224
	s_nop 1
	v_permlane32_swap_b32_e32 v224, v225
	v_max_f32_e32 v224, v224, v225
	v_cmp_lt_f32_e32 vcc, s92, v224
	s_or_b64 vcc, s[22:23], vcc
	s_cbranch_vccz .LBB0_652
	v_cmp_lt_f32_e32 vcc, 0, v224
	s_or_b64 vcc, s[22:23], vcc
	s_nop 0
	v_cndmask_b32_e32 v225, 0, v224, vcc
	v_exp_f32_e64 v224, -v225
	v_add_f32_e32 v168, v168, v225
	v_sub_f32_e32 v228, v228, v225
	v_sub_f32_e32 v229, v229, v225
	v_sub_f32_e32 v230, v230, v225
	v_sub_f32_e32 v231, v231, v225
	v_sub_f32_e32 v232, v232, v225
	v_sub_f32_e32 v233, v233, v225
	v_sub_f32_e32 v234, v234, v225
	v_sub_f32_e32 v235, v235, v225
	v_sub_f32_e32 v236, v236, v225
	v_sub_f32_e32 v237, v237, v225
	v_sub_f32_e32 v238, v238, v225
	v_sub_f32_e32 v239, v239, v225
	v_sub_f32_e32 v240, v240, v225
	v_sub_f32_e32 v241, v241, v225
	v_sub_f32_e32 v242, v242, v225
	v_sub_f32_e32 v243, v243, v225
	v_sub_f32_e32 v96, v96, v225
	v_sub_f32_e32 v97, v97, v225
	v_cndmask_b32_e64 v224, v224, 0, s[22:23]
	v_mul_f32_e32 v0, v0, v224
	v_pk_mul_f32 v[78:79], v[78:79], v[224:225] op_sel_hi:[1, 0]
	v_pk_mul_f32 v[76:77], v[76:77], v[224:225] op_sel_hi:[1, 0]
	v_pk_mul_f32 v[74:75], v[74:75], v[224:225] op_sel_hi:[1, 0]
	v_pk_mul_f32 v[72:73], v[72:73], v[224:225] op_sel_hi:[1, 0]
	v_pk_mul_f32 v[70:71], v[70:71], v[224:225] op_sel_hi:[1, 0]
	v_pk_mul_f32 v[68:69], v[68:69], v[224:225] op_sel_hi:[1, 0]
	v_pk_mul_f32 v[66:67], v[66:67], v[224:225] op_sel_hi:[1, 0]
	v_pk_mul_f32 v[64:65], v[64:65], v[224:225] op_sel_hi:[1, 0]
	v_pk_mul_f32 v[62:63], v[62:63], v[224:225] op_sel_hi:[1, 0]
	v_pk_mul_f32 v[60:61], v[60:61], v[224:225] op_sel_hi:[1, 0]
	v_pk_mul_f32 v[58:59], v[58:59], v[224:225] op_sel_hi:[1, 0]
	v_pk_mul_f32 v[56:57], v[56:57], v[224:225] op_sel_hi:[1, 0]
	v_pk_mul_f32 v[54:55], v[54:55], v[224:225] op_sel_hi:[1, 0]
	v_pk_mul_f32 v[52:53], v[52:53], v[224:225] op_sel_hi:[1, 0]
	v_pk_mul_f32 v[50:51], v[50:51], v[224:225] op_sel_hi:[1, 0]
	v_pk_mul_f32 v[48:49], v[48:49], v[224:225] op_sel_hi:[1, 0]
	v_pk_mul_f32 v[46:47], v[46:47], v[224:225] op_sel_hi:[1, 0]
	v_pk_mul_f32 v[44:45], v[44:45], v[224:225] op_sel_hi:[1, 0]
	v_pk_mul_f32 v[42:43], v[42:43], v[224:225] op_sel_hi:[1, 0]
	v_pk_mul_f32 v[40:41], v[40:41], v[224:225] op_sel_hi:[1, 0]
	v_pk_mul_f32 v[38:39], v[38:39], v[224:225] op_sel_hi:[1, 0]
	v_pk_mul_f32 v[36:37], v[36:37], v[224:225] op_sel_hi:[1, 0]
	v_pk_mul_f32 v[34:35], v[34:35], v[224:225] op_sel_hi:[1, 0]
	v_pk_mul_f32 v[32:33], v[32:33], v[224:225] op_sel_hi:[1, 0]
	v_pk_mul_f32 v[30:31], v[30:31], v[224:225] op_sel_hi:[1, 0]
	v_pk_mul_f32 v[28:29], v[28:29], v[224:225] op_sel_hi:[1, 0]
	v_pk_mul_f32 v[26:27], v[26:27], v[224:225] op_sel_hi:[1, 0]
	v_pk_mul_f32 v[24:25], v[24:25], v[224:225] op_sel_hi:[1, 0]
	v_pk_mul_f32 v[22:23], v[22:23], v[224:225] op_sel_hi:[1, 0]
	v_pk_mul_f32 v[20:21], v[20:21], v[224:225] op_sel_hi:[1, 0]
	v_pk_mul_f32 v[18:19], v[18:19], v[224:225] op_sel_hi:[1, 0]
	v_pk_mul_f32 v[16:17], v[16:17], v[224:225] op_sel_hi:[1, 0]
	v_sub_f32_e32 v98, v98, v225
	v_sub_f32_e32 v99, v99, v225
	v_sub_f32_e32 v100, v100, v225
	v_sub_f32_e32 v101, v101, v225
	v_sub_f32_e32 v102, v102, v225
	v_sub_f32_e32 v103, v103, v225
	v_sub_f32_e32 v104, v104, v225
	v_sub_f32_e32 v105, v105, v225
	v_sub_f32_e32 v106, v106, v225
	v_sub_f32_e32 v107, v107, v225
	v_sub_f32_e32 v108, v108, v225
	v_sub_f32_e32 v109, v109, v225
	v_sub_f32_e32 v110, v110, v225
	v_sub_f32_e32 v111, v111, v225
	v_sub_f32_e32 v80, v80, v225
	v_sub_f32_e32 v81, v81, v225
	v_sub_f32_e32 v82, v82, v225
	v_sub_f32_e32 v83, v83, v225
	v_sub_f32_e32 v84, v84, v225
	v_sub_f32_e32 v85, v85, v225
	v_sub_f32_e32 v86, v86, v225
	v_sub_f32_e32 v87, v87, v225
	v_sub_f32_e32 v88, v88, v225
	v_sub_f32_e32 v89, v89, v225
	v_sub_f32_e32 v90, v90, v225
	v_sub_f32_e32 v91, v91, v225
	v_sub_f32_e32 v92, v92, v225
	v_sub_f32_e32 v93, v93, v225
	v_sub_f32_e32 v94, v94, v225
	v_sub_f32_e32 v95, v95, v225
; template <int DVT, bool FOX>
; DI void attn_step(const char* kb, const bf16x8 (&qf)[4], f32x16 (&o)[DVT], float& m, float& l, const bool diag, const int j, const int tq, const int r, const int hh) {
;     ...
;   f32x2 ls2 = {0.f, 0.f};
; #pragma unroll
;   for (int kt = 0; kt < 2; ++kt)
; #pragma unroll
;     for (int i = 0; i < 8; ++i) {
;       f32x2 pv = {__builtin_amdgcn_exp2f(st[kt][2 * i]), __builtin_amdgcn_exp2f(st[kt][2 * i + 1])};
;       st[kt][2 * i] = pv[0]; st[kt][2 * i + 1] = pv[1];
;       ls2 = ls2 + pv;
;     }
;   l += ls2[0] + ls2[1];
;   __builtin_amdgcn_sched_barrier(0);
;     ...
;   A_PVGROUP(0, va, vn); A_PVGROUP(1, vn, va); A_PVGROUP(2, va, vn); A_PVGROUP(3, vn, va);
.LBB0_652:
	v_exp_f32_e32 v96, v96
	v_exp_f32_e32 v97, v97
	v_exp_f32_e32 v98, v98
	v_exp_f32_e32 v99, v99
	v_pk_add_f32 v[224:225], v[96:97], 0 op_sel_hi:[1,0]
	v_exp_f32_e32 v100, v100
	v_exp_f32_e32 v101, v101
	v_pk_add_f32 v[224:225], v[98:99], v[224:225]
	v_exp_f32_e32 v102, v102
	v_exp_f32_e32 v103, v103
	v_pk_add_f32 v[224:225], v[100:101], v[224:225]
	v_exp_f32_e32 v104, v104
	v_exp_f32_e32 v105, v105
	v_pk_add_f32 v[224:225], v[102:103], v[224:225]
	v_exp_f32_e32 v106, v106
	v_exp_f32_e32 v107, v107
	v_pk_add_f32 v[224:225], v[104:105], v[224:225]
	v_exp_f32_e32 v108, v108
	v_exp_f32_e32 v109, v109
	v_pk_add_f32 v[224:225], v[106:107], v[224:225]
	v_exp_f32_e32 v110, v110
	v_exp_f32_e32 v111, v111
	v_pk_add_f32 v[224:225], v[108:109], v[224:225]
	v_exp_f32_e32 v80, v80
	v_exp_f32_e32 v81, v81
	v_pk_add_f32 v[224:225], v[110:111], v[224:225]
	v_exp_f32_e32 v82, v82
	v_exp_f32_e32 v83, v83
	v_pk_add_f32 v[224:225], v[80:81], v[224:225]
	v_exp_f32_e32 v84, v84
	v_exp_f32_e32 v85, v85
	v_pk_add_f32 v[224:225], v[82:83], v[224:225]
	v_exp_f32_e32 v86, v86
	v_exp_f32_e32 v87, v87
	v_pk_add_f32 v[224:225], v[84:85], v[224:225]
	v_exp_f32_e32 v88, v88
	v_exp_f32_e32 v89, v89
	v_pk_add_f32 v[224:225], v[86:87], v[224:225]
	v_exp_f32_e32 v90, v90
	v_exp_f32_e32 v91, v91
	v_pk_add_f32 v[224:225], v[88:89], v[224:225]
	v_exp_f32_e32 v92, v92
	v_exp_f32_e32 v93, v93
	v_pk_add_f32 v[224:225], v[90:91], v[224:225]
	v_exp_f32_e32 v94, v94
	v_exp_f32_e32 v95, v95
	v_pk_add_f32 v[224:225], v[92:93], v[224:225]
	s_nop 0
	v_pk_add_f32 v[224:225], v[94:95], v[224:225]
	v_cvt_pk_bf16_f32 v244, v96, v97
	v_cvt_pk_bf16_f32 v245, v98, v99
	v_cvt_pk_bf16_f32 v246, v100, v101
	v_cvt_pk_bf16_f32 v247, v102, v103
	v_cvt_pk_bf16_f32 v248, v104, v105
	v_cvt_pk_bf16_f32 v249, v106, v107
	v_cvt_pk_bf16_f32 v250, v108, v109
	v_cvt_pk_bf16_f32 v251, v110, v111
	v_cvt_pk_bf16_f32 v212, v80, v81
	v_cvt_pk_bf16_f32 v213, v82, v83
	v_cvt_pk_bf16_f32 v214, v84, v85
	v_cvt_pk_bf16_f32 v215, v86, v87
	v_cvt_pk_bf16_f32 v218, v88, v89
	v_cvt_pk_bf16_f32 v219, v90, v91
	v_cvt_pk_bf16_f32 v220, v92, v93
	v_cvt_pk_bf16_f32 v221, v94, v95
	v_add_f32_e32 v224, v224, v225
	s_nop 0
	v_add_f32_e32 v0, v0, v224
	ds_read_b128 v[80:83], v184 offset:37152
	ds_read_b128 v[84:87], v184 offset:41760
	ds_read_b128 v[88:91], v184 offset:46368
	ds_read_b128 v[92:95], v184 offset:50976
	s_waitcnt lgkmcnt(7)
	v_mfma_f32_32x32x16_bf16 v[64:79], v[152:155], v[244:247], v[64:79]
	s_waitcnt lgkmcnt(6)
	v_mfma_f32_32x32x16_bf16 v[48:63], v[10:13], v[244:247], v[48:63]
	s_waitcnt lgkmcnt(5)
	v_mfma_f32_32x32x16_bf16 v[32:47], v[6:9], v[244:247], v[32:47]
	s_waitcnt lgkmcnt(4)
	v_mfma_f32_32x32x16_bf16 v[16:31], v[2:5], v[244:247], v[16:31]
	ds_read_b128 v[2:5], v184 offset:37184
	ds_read_b128 v[6:9], v184 offset:41792
	ds_read_b128 v[10:13], v184 offset:46400
	ds_read_b128 v[96:99], v184 offset:51008
	s_waitcnt lgkmcnt(7)
	v_mfma_f32_32x32x16_bf16 v[64:79], v[80:83], v[248:251], v[64:79]
	s_waitcnt lgkmcnt(6)
	v_mfma_f32_32x32x16_bf16 v[48:63], v[84:87], v[248:251], v[48:63]
	s_waitcnt lgkmcnt(5)
	v_mfma_f32_32x32x16_bf16 v[32:47], v[88:91], v[248:251], v[32:47]
	s_waitcnt lgkmcnt(4)
	v_mfma_f32_32x32x16_bf16 v[16:31], v[92:95], v[248:251], v[16:31]
	ds_read_b128 v[80:83], v184 offset:37216
	ds_read_b128 v[84:87], v184 offset:41824
	ds_read_b128 v[88:91], v184 offset:46432
	ds_read_b128 v[92:95], v184 offset:51040
	s_waitcnt lgkmcnt(7)
	v_mfma_f32_32x32x16_bf16 v[64:79], v[2:5], v[212:215], v[64:79]
	s_waitcnt lgkmcnt(6)
	v_mfma_f32_32x32x16_bf16 v[48:63], v[6:9], v[212:215], v[48:63]
	s_waitcnt lgkmcnt(5)
	v_mfma_f32_32x32x16_bf16 v[32:47], v[10:13], v[212:215], v[32:47]
	s_waitcnt lgkmcnt(4)
	v_mfma_f32_32x32x16_bf16 v[16:31], v[96:99], v[212:215], v[16:31]
	s_waitcnt lgkmcnt(3)
	v_mfma_f32_32x32x16_bf16 v[64:79], v[80:83], v[218:221], v[64:79]
	s_waitcnt lgkmcnt(2)
	v_mfma_f32_32x32x16_bf16 v[48:63], v[84:87], v[218:221], v[48:63]
	s_waitcnt lgkmcnt(1)
	v_mfma_f32_32x32x16_bf16 v[32:47], v[88:91], v[218:221], v[32:47]
	s_waitcnt lgkmcnt(0)
	v_mfma_f32_32x32x16_bf16 v[16:31], v[92:95], v[218:221], v[16:31]
	s_cmp_eq_u32 s2, 0
	s_cbranch_scc0 .LBB0_639
; DI unsigned pk2(float lo, float hi) { f32x2 v = {lo, hi}; bf16x2v b = __builtin_convertvector(v, bf16x2v); return __builtin_bit_cast(unsigned, b); }
; #define A_GLOAD(KR, VR, CR, JT) { const int s1_ = (JT) * 64; KR = *(const u32x4*)(kp + (size_t)s1_ * ldk); \
;     _Pragma("unroll") for (int i_ = 0; i_ < DVT / 2; ++i_) VR[i_] = *(const u32x4*)(vp + (size_t)(64 * i_) * SEQ + s1_); \
;     if (FOX) { if (tid < 16) { f32x4 t_ = *(const f32x4*)(cbase + s1_ + tid * 4); CR[0] = -t_[0]; CR[1] = -t_[1]; CR[2] = -t_[2]; CR[3] = -t_[3]; } } }
; template <int DVT, bool FOX> ...
;     ...
;   for (int ks = 0; ks < 4; ++ks) qf[ks] = *(const bf16x8*)(qrow + ks * 16 + hh * 8);
; #pragma unroll
;   for (int d = 0; d < DVT; ++d)
; #pragma unroll
;     for (int i = 0; i < 16; ++i) o[d][i] = 0.f;
;   float m = 0.f, l = 0.f;
;   u32x4 kr0, kr1, vr0[DVT / 2], vr1[DVT / 2]; f32x4 cr0 = {0.f, 0.f, 0.f, 0.f}, cr1 = {0.f, 0.f, 0.f, 0.f};
;   const bf16_t* kp = kbase + (size_t)lrow * ldk + lch * 8;
;   const bf16_t* vp = vtbase + (size_t)lrow * SEQ + lch * 8;
;     ...
;   int j = j_hi;
;   A_GLOAD(kr0, vr0, cr0, j);
;   if (j >= 1) A_GLOAD(kr1, vr1, cr1, j - 1);
; DI void diff_phase(const Params& p, const int j_even, char* lds) {
;     ...
;       const float i1 = 1.f / l1;
;       unsigned* o1s = (unsigned*)(lds + DIFF_STASH_OFF) + tid;
; #pragma unroll
;       for (int d = 0; d < 4; ++d)
; #pragma unroll
;         for (int i = 0; i < 8; ++i) o1s[(d * 8 + i) * 512] = pk2(o1[d][2 * i] * i1, o1[d][2 * i + 1] * i1);
.LBB0_653:
.LBB0_654:
	v_mov_b32_e32 v2, v0
	s_nop 1
	v_permlane32_swap_b32_e32 v0, v2
	v_add_f32_e32 v0, v0, v2
	v_div_scale_f32 v2, s[2:3], v0, v0, 1.0
	v_rcp_f32_e32 v3, v2
	s_barrier
	v_fma_f32 v4, -v2, v3, 1.0
	v_fmac_f32_e32 v3, v4, v3
	v_div_scale_f32 v4, vcc, 1.0, v0, 1.0
	v_mul_f32_e32 v5, v4, v3
	v_fma_f32 v6, -v2, v5, v4
	v_fmac_f32_e32 v5, v6, v3
	v_fma_f32 v2, -v2, v5, v4
	v_div_fmas_f32 v2, v2, v3, v5
	v_div_fixup_f32 v0, v2, v0, 1.0
	v_pk_mul_f32 v[2:3], v[64:65], v[0:1] op_sel_hi:[1,0]
	v_mov_b32_e32 v5, v192
	v_cvt_pk_bf16_f32 v4, v2, v3
	v_pk_mul_f32 v[2:3], v[66:67], v[0:1] op_sel_hi:[1,0]
	v_mov_b32_e32 v166, 0
	v_mov_b32_e32 v228, 0
	v_mov_b32_e32 v229, 0
	v_mov_b32_e32 v230, 0
	v_mov_b32_e32 v231, 0
	v_mov_b32_e32 v232, 0
	v_mov_b32_e32 v233, 0
	v_mov_b32_e32 v234, 0
	v_mov_b32_e32 v235, 0
	v_mov_b32_e32 v236, 0
	v_mov_b32_e32 v237, 0
	v_mov_b32_e32 v238, 0
	v_mov_b32_e32 v239, 0
	v_mov_b32_e32 v240, 0
	v_mov_b32_e32 v241, 0
	v_mov_b32_e32 v242, 0
	v_mov_b32_e32 v243, 0
	v_cvt_pk_bf16_f32 v2, v2, v3
	ds_write2st64_b32 v180, v4, v2 offset0:218 offset1:226
	v_pk_mul_f32 v[2:3], v[68:69], v[0:1] op_sel_hi:[1,0]
	s_waitcnt vmcnt(1)
	v_mov_b32_e32 v144, 0
	v_cvt_pk_bf16_f32 v4, v2, v3
	v_pk_mul_f32 v[2:3], v[70:71], v[0:1] op_sel_hi:[1,0]
	v_mov_b32_e32 v145, 0
	v_cvt_pk_bf16_f32 v2, v2, v3
	ds_write2st64_b32 v180, v4, v2 offset0:234 offset1:242
	v_pk_mul_f32 v[2:3], v[72:73], v[0:1] op_sel_hi:[1,0]
	v_mov_b32_e32 v146, 0
	v_cvt_pk_bf16_f32 v2, v2, v3
	ds_write_b32 v180, v2 offset:64000
	v_pk_mul_f32 v[2:3], v[74:75], v[0:1] op_sel_hi:[1,0]
	v_mov_b32_e32 v147, 0
	v_cvt_pk_bf16_f32 v4, v2, v3
	v_pk_mul_f32 v[2:3], v[76:77], v[0:1] op_sel_hi:[1,0]
	s_waitcnt vmcnt(0)
	v_mov_b32_e32 v148, 0
	v_cvt_pk_bf16_f32 v2, v2, v3
	ds_write2st64_b32 v181, v4, v2 offset0:40 offset1:48
	v_pk_mul_f32 v[2:3], v[78:79], v[0:1] op_sel_hi:[1,0]
	v_mov_b32_e32 v149, 0
	v_cvt_pk_bf16_f32 v4, v2, v3
	v_pk_mul_f32 v[2:3], v[48:49], v[0:1] op_sel_hi:[1,0]
	v_mov_b32_e32 v150, 0
	v_cvt_pk_bf16_f32 v2, v2, v3
	ds_write2st64_b32 v181, v4, v2 offset0:56 offset1:64
	v_pk_mul_f32 v[2:3], v[50:51], v[0:1] op_sel_hi:[1,0]
	v_mov_b32_e32 v151, 0
	v_cvt_pk_bf16_f32 v4, v2, v3
	v_pk_mul_f32 v[2:3], v[52:53], v[0:1] op_sel_hi:[1,0]
	s_nop 0
	v_cvt_pk_bf16_f32 v2, v2, v3
	ds_write2st64_b32 v181, v4, v2 offset0:72 offset1:80
	v_pk_mul_f32 v[2:3], v[54:55], v[0:1] op_sel_hi:[1,0]
	s_nop 0
	v_cvt_pk_bf16_f32 v4, v2, v3
	v_pk_mul_f32 v[2:3], v[56:57], v[0:1] op_sel_hi:[1,0]
	s_nop 0
	v_cvt_pk_bf16_f32 v2, v2, v3
	ds_write2st64_b32 v181, v4, v2 offset0:88 offset1:96
	v_pk_mul_f32 v[2:3], v[58:59], v[0:1] op_sel_hi:[1,0]
	s_nop 0
	v_cvt_pk_bf16_f32 v4, v2, v3
	v_pk_mul_f32 v[2:3], v[60:61], v[0:1] op_sel_hi:[1,0]
	s_nop 0
	v_cvt_pk_bf16_f32 v2, v2, v3
	ds_write2st64_b32 v181, v4, v2 offset0:104 offset1:112
	v_pk_mul_f32 v[2:3], v[62:63], v[0:1] op_sel_hi:[1,0]
	s_nop 0
	v_cvt_pk_bf16_f32 v4, v2, v3
	v_pk_mul_f32 v[2:3], v[32:33], v[0:1] op_sel_hi:[1,0]
	s_nop 0
	v_cvt_pk_bf16_f32 v2, v2, v3
	ds_write2st64_b32 v181, v4, v2 offset0:120 offset1:128
	v_pk_mul_f32 v[2:3], v[34:35], v[0:1] op_sel_hi:[1,0]
	s_nop 0
	v_cvt_pk_bf16_f32 v4, v2, v3
	v_pk_mul_f32 v[2:3], v[36:37], v[0:1] op_sel_hi:[1,0]
	s_nop 0
	v_cvt_pk_bf16_f32 v2, v2, v3
	ds_write2st64_b32 v181, v4, v2 offset0:136 offset1:144
	v_pk_mul_f32 v[2:3], v[38:39], v[0:1] op_sel_hi:[1,0]
	s_nop 0
	v_cvt_pk_bf16_f32 v4, v2, v3
	v_pk_mul_f32 v[2:3], v[40:41], v[0:1] op_sel_hi:[1,0]
	s_nop 0
	v_cvt_pk_bf16_f32 v2, v2, v3
	ds_write2st64_b32 v181, v4, v2 offset0:152 offset1:160
	v_pk_mul_f32 v[2:3], v[42:43], v[0:1] op_sel_hi:[1,0]
	s_nop 0
	v_cvt_pk_bf16_f32 v4, v2, v3
	v_pk_mul_f32 v[2:3], v[44:45], v[0:1] op_sel_hi:[1,0]
	s_nop 0
	v_cvt_pk_bf16_f32 v2, v2, v3
	ds_write2st64_b32 v181, v4, v2 offset0:168 offset1:176
	v_pk_mul_f32 v[2:3], v[46:47], v[0:1] op_sel_hi:[1,0]
	s_nop 0
	v_cvt_pk_bf16_f32 v4, v2, v3
	v_pk_mul_f32 v[2:3], v[16:17], v[0:1] op_sel_hi:[1,0]
	s_nop 0
	v_cvt_pk_bf16_f32 v2, v2, v3
	ds_write2st64_b32 v181, v4, v2 offset0:184 offset1:192
	v_pk_mul_f32 v[2:3], v[18:19], v[0:1] op_sel_hi:[1,0]
	s_nop 0
	v_cvt_pk_bf16_f32 v4, v2, v3
	v_pk_mul_f32 v[2:3], v[20:21], v[0:1] op_sel_hi:[1,0]
	s_nop 0
	v_cvt_pk_bf16_f32 v2, v2, v3
	ds_write2st64_b32 v181, v4, v2 offset0:200 offset1:208
	v_pk_mul_f32 v[2:3], v[22:23], v[0:1] op_sel_hi:[1,0]
	s_nop 0
	v_cvt_pk_bf16_f32 v4, v2, v3
	v_pk_mul_f32 v[2:3], v[24:25], v[0:1] op_sel_hi:[1,0]
	s_nop 0
	v_cvt_pk_bf16_f32 v2, v2, v3
	ds_write2st64_b32 v181, v4, v2 offset0:216 offset1:224
	v_pk_mul_f32 v[2:3], v[26:27], v[0:1] op_sel_hi:[1,0]
	s_nop 0
	v_cvt_pk_bf16_f32 v4, v2, v3
	v_pk_mul_f32 v[2:3], v[28:29], v[0:1] op_sel_hi:[1,0]
	s_nop 0
	v_cvt_pk_bf16_f32 v2, v2, v3
	ds_write2st64_b32 v181, v4, v2 offset0:232 offset1:240
	v_pk_mul_f32 v[2:3], v[30:31], v[0:1] op_sel_hi:[1,0]
	s_nop 0
	v_cvt_pk_bf16_f32 v0, v2, v3
	ds_write_b32 v181, v0 offset:63488
	s_nop 0
	v_bfe_u32 v4, v5, 5, 1
	v_ashrrev_i32_e32 v2, 3, v5
	v_lshlrev_b32_e32 v0, 4, v4
	v_lshl_add_u64 v[6:7], v[162:163], 0, v[0:1]
	v_ashrrev_i32_e32 v3, 31, v2
	global_load_dwordx4 v[112:115], v[6:7], off offset:128
	global_load_dwordx4 v[116:119], v[6:7], off offset:160
	global_load_dwordx4 v[120:123], v[6:7], off offset:192
	global_load_dwordx4 v[124:127], v[6:7], off offset:224
	v_and_b32_e32 v0, 7, v5
	v_lshlrev_b64 v[6:7], 10, v[2:3]
	v_lshl_add_u64 v[6:7], s[8:9], 0, v[6:7]
	v_lshlrev_b32_e32 v0, 4, v0
	v_lshl_add_u64 v[162:163], v[6:7], 0, v[0:1]
	v_lshlrev_b64 v[6:7], 15, v[2:3]
	v_lshl_add_u64 v[6:7], s[10:11], 0, v[6:7]
	v_lshl_add_u64 v[164:165], v[6:7], 0, v[0:1]
	v_subrev_u32_e32 v217, s8, v162
	v_subrev_u32_e32 v222, s10, v164
	v_add_u32_e32 v227, 0x200000, v222
	v_lshl_add_u64 v[6:7], v[162:163], 0, s[16:17]
	v_lshl_add_u64 v[8:9], s[4:5], 1, v[164:165]
	global_load_dwordx4 v[128:131], v[6:7], off offset:128
	global_load_dwordx4 v[132:135], v[8:9], off
	v_add_co_u32_e32 v6, vcc, 0x200000, v8
	s_nop 1
	v_addc_co_u32_e32 v7, vcc, 0, v9, vcc
	global_load_dwordx4 v[136:139], v[6:7], off
	s_andn2_b64 vcc, exec, s[18:19]
	s_cbranch_vccnz .LBB0_656
	s_sub_i32 s96, s4, 64
	s_lshl_b64 s[2:3], s[96:97], 10
	v_lshl_add_u64 v[6:7], v[162:163], 0, s[2:3]
	v_lshl_add_u64 v[8:9], s[96:97], 1, v[164:165]
	global_load_dwordx4 v[140:143], v[6:7], off offset:128
	global_load_dwordx4 v[144:147], v[8:9], off
	v_add_co_u32_e32 v6, vcc, 0x200000, v8
	s_nop 1
	v_addc_co_u32_e32 v7, vcc, 0, v9, vcc
	global_load_dwordx4 v[148:151], v[6:7], off

; #define MFMA32(a, b, c) __builtin_amdgcn_mfma_f32_32x32x16_bf16((a), (b), (c), 0, 0, 0)
; DI float xmax32(float v) { const u32x2 r_ = __builtin_amdgcn_permlane32_swap(__float_as_uint(v), __float_as_uint(v), false, false); return fmaxf(__uint_as_float(r_[0]), __uint_as_float(r_[1])); }
; template <int DVT, bool FOX>
; DI void attn_step(const char* kb, const bf16x8 (&qf)[4], f32x16 (&o)[DVT], float& m, float& l, const bool diag, const int j, const int tq, const int r, const int hh) {
;     ...
; #pragma unroll
;   for (int ks = 0; ks < 4; ++ks)
; #pragma unroll
;     for (int kt = 0; kt < 2; ++kt) st[kt] = MFMA32(kf[ks * 2 + kt], qf[ks], st[kt]);
;   bf16x8 va[DVT], vn[DVT];
; #pragma unroll
;   for (int d = 0; d < DVT; ++d) va[d] = *(const bf16x8*)(vb + (d * 32 + r) * LROW + (8 * hh) * 2);
;   __builtin_amdgcn_sched_barrier(0);
;   {
;     const f32x2 mm = {m, m};
; #pragma unroll
;     for (int kt = 0; kt < 2; ++kt)
; #pragma unroll
;       for (int i = 0; i < 8; ++i) { f32x2 z = {st[kt][2 * i], st[kt][2 * i + 1]}; z = z - mm; st[kt][2 * i] = z[0]; st[kt][2 * i + 1] = z[1]; }
;   }
;   if (FOX) {
;     if (diag) {
; #pragma unroll
;       for (int kt = 0; kt < 2; ++kt)
; #pragma unroll
;         for (int i = 0; i < 16; ++i) {
;           const int key = j * 64 + kt * 32 + (i & 3) + 8 * (i >> 2) + 4 * hh;
;           if (key > tq) st[kt][i] = -INFINITY;
;         }
;     }
;   }
;   float mx;
;   {
;     float a0 = fmaxf(fmaxf(st[0][0], st[0][1]), st[0][2]), a1 = fmaxf(fmaxf(st[1][0], st[1][1]), st[1][2]);
; #pragma unroll
;     for (int i = 3; i < 15; i += 2) { a0 = fmaxf(fmaxf(a0, st[0][i]), st[0][i + 1]); a1 = fmaxf(fmaxf(a1, st[1][i]), st[1][i + 1]); }
;     mx = fmaxf(fmaxf(a0, a1), fmaxf(st[0][15], st[1][15]));
;   }
;   mx = xmax32(mx);
;   if (__any(diag || mx > 8.f)) {
;     const float d = (diag || mx > 0.f) ? mx : 0.f;
;     const float alpha = diag ? 0.f : __builtin_amdgcn_exp2f(-d);
;     m += d;
;     l *= alpha;
; #pragma unroll
;     for (int dd = 0; dd < DVT; ++dd)
; #pragma unroll
;       for (int i = 0; i < 16; ++i) o[dd][i] *= alpha;
;     const f32x2 d2 = {d, d};
; #pragma unroll
;     for (int kt = 0; kt < 2; ++kt)
; #pragma unroll
;       for (int i = 0; i < 8; ++i) { f32x2 z = {st[kt][2 * i], st[kt][2 * i + 1]}; z = z - d2; st[kt][2 * i] = z[0]; st[kt][2 * i + 1] = z[1]; }
;   }
.LBB0_660:
	s_add_i32 s3, s26, s27
	s_cmp_gt_i32 s2, s25
	s_cbranch_scc1 .LBB0_664
	ds_read_b128 v[2:5], v177
	ds_read_b128 v[6:9], v177 offset:32
	ds_read_b128 v[10:13], v177 offset:4608
	ds_read_b128 v[152:155], v177 offset:4640
	ds_read_b128 v[168:171], v177 offset:64
	ds_read_b128 v[172:175], v177 offset:96
	ds_read_b128 v[184:187], v177 offset:4672
	ds_read_b128 v[188:191], v177 offset:4704
	s_cmp_eq_u32 s3, -1
	s_cselect_b64 s[4:5], -1, 0
	s_waitcnt lgkmcnt(7)
	v_mfma_f32_32x32x16_bf16 v[96:111], v[2:5], v[112:115], v[228:243]
	s_waitcnt lgkmcnt(5)
	v_mfma_f32_32x32x16_bf16 v[80:95], v[10:13], v[112:115], v[228:243]
	v_mfma_f32_32x32x16_bf16 v[96:111], v[6:9], v[116:119], v[96:111]
	s_waitcnt lgkmcnt(4)
	v_mfma_f32_32x32x16_bf16 v[80:95], v[152:155], v[116:119], v[80:95]
	ds_read_b128 v[152:155], v177 offset:9216
	ds_read_b128 v[10:13], v177 offset:13824
	ds_read_b128 v[6:9], v177 offset:18432
	ds_read_b128 v[2:5], v177 offset:23040
	s_waitcnt lgkmcnt(7)
	v_mfma_f32_32x32x16_bf16 v[96:111], v[168:171], v[120:123], v[96:111]
	s_waitcnt lgkmcnt(5)
	v_mfma_f32_32x32x16_bf16 v[80:95], v[184:187], v[120:123], v[80:95]
	v_mfma_f32_32x32x16_bf16 v[96:111], v[172:175], v[124:127], v[96:111]
	s_waitcnt lgkmcnt(4)
	v_mfma_f32_32x32x16_bf16 v[80:95], v[188:191], v[124:127], v[80:95]
	s_nop 10
	v_max3_f32 v224, v96, v97, v98
	v_max3_f32 v225, v80, v81, v82
	v_max3_f32 v224, v224, v99, v100
	v_max3_f32 v225, v225, v83, v84
	v_max3_f32 v224, v224, v101, v102
	v_max3_f32 v225, v225, v85, v86
	v_max3_f32 v224, v224, v103, v104
	v_max3_f32 v225, v225, v87, v88
	v_max3_f32 v224, v224, v105, v106
	v_max3_f32 v225, v225, v89, v90
	v_max3_f32 v224, v224, v107, v108
	v_max3_f32 v225, v225, v91, v92
	v_max3_f32 v224, v224, v109, v110
	v_max3_f32 v225, v225, v93, v94
	v_max_f32_e32 v226, v111, v95
	v_max3_f32 v224, v224, v225, v226
	v_mov_b32_e32 v225, v224
	s_nop 1
	v_permlane32_swap_b32_e32 v224, v225
	v_max_f32_e32 v224, v224, v225
	v_cmp_lt_f32_e32 vcc, s92, v224
	s_or_b64 vcc, s[4:5], vcc
	s_cbranch_vccz .LBB0_663
	v_cmp_lt_f32_e32 vcc, 0, v224
	s_or_b64 vcc, s[4:5], vcc
	s_nop 0
	v_cndmask_b32_e32 v225, 0, v224, vcc
	v_exp_f32_e64 v224, -v225
	v_add_f32_e32 v166, v166, v225
	v_sub_f32_e32 v228, v228, v225
	v_sub_f32_e32 v229, v229, v225
	v_sub_f32_e32 v230, v230, v225
	v_sub_f32_e32 v231, v231, v225
	v_sub_f32_e32 v232, v232, v225
	v_sub_f32_e32 v233, v233, v225
	v_sub_f32_e32 v234, v234, v225
	v_sub_f32_e32 v235, v235, v225
	v_sub_f32_e32 v236, v236, v225
	v_sub_f32_e32 v237, v237, v225
	v_sub_f32_e32 v238, v238, v225
	v_sub_f32_e32 v239, v239, v225
	v_sub_f32_e32 v240, v240, v225
	v_sub_f32_e32 v241, v241, v225
	v_sub_f32_e32 v242, v242, v225
	v_sub_f32_e32 v243, v243, v225
	v_sub_f32_e32 v96, v96, v225
	v_sub_f32_e32 v97, v97, v225
	v_cndmask_b32_e64 v224, v224, 0, s[4:5]
	v_mul_f32_e32 v0, v0, v224
	v_pk_mul_f32 v[78:79], v[78:79], v[224:225] op_sel_hi:[1, 0]
	v_pk_mul_f32 v[76:77], v[76:77], v[224:225] op_sel_hi:[1, 0]
	v_pk_mul_f32 v[74:75], v[74:75], v[224:225] op_sel_hi:[1, 0]
	v_pk_mul_f32 v[72:73], v[72:73], v[224:225] op_sel_hi:[1, 0]
	v_pk_mul_f32 v[70:71], v[70:71], v[224:225] op_sel_hi:[1, 0]
	v_pk_mul_f32 v[68:69], v[68:69], v[224:225] op_sel_hi:[1, 0]
	v_pk_mul_f32 v[66:67], v[66:67], v[224:225] op_sel_hi:[1, 0]
	v_pk_mul_f32 v[64:65], v[64:65], v[224:225] op_sel_hi:[1, 0]
	v_pk_mul_f32 v[62:63], v[62:63], v[224:225] op_sel_hi:[1, 0]
	v_pk_mul_f32 v[60:61], v[60:61], v[224:225] op_sel_hi:[1, 0]
	v_pk_mul_f32 v[58:59], v[58:59], v[224:225] op_sel_hi:[1, 0]
	v_pk_mul_f32 v[56:57], v[56:57], v[224:225] op_sel_hi:[1, 0]
	v_pk_mul_f32 v[54:55], v[54:55], v[224:225] op_sel_hi:[1, 0]
	v_pk_mul_f32 v[52:53], v[52:53], v[224:225] op_sel_hi:[1, 0]
	v_pk_mul_f32 v[50:51], v[50:51], v[224:225] op_sel_hi:[1, 0]
	v_pk_mul_f32 v[48:49], v[48:49], v[224:225] op_sel_hi:[1, 0]
	v_pk_mul_f32 v[46:47], v[46:47], v[224:225] op_sel_hi:[1, 0]
	v_pk_mul_f32 v[44:45], v[44:45], v[224:225] op_sel_hi:[1, 0]
	v_pk_mul_f32 v[42:43], v[42:43], v[224:225] op_sel_hi:[1, 0]
	v_pk_mul_f32 v[40:41], v[40:41], v[224:225] op_sel_hi:[1, 0]
	v_pk_mul_f32 v[38:39], v[38:39], v[224:225] op_sel_hi:[1, 0]
	v_pk_mul_f32 v[36:37], v[36:37], v[224:225] op_sel_hi:[1, 0]
	v_pk_mul_f32 v[34:35], v[34:35], v[224:225] op_sel_hi:[1, 0]
	v_pk_mul_f32 v[32:33], v[32:33], v[224:225] op_sel_hi:[1, 0]
	v_pk_mul_f32 v[30:31], v[30:31], v[224:225] op_sel_hi:[1, 0]
	v_pk_mul_f32 v[28:29], v[28:29], v[224:225] op_sel_hi:[1, 0]
	v_pk_mul_f32 v[26:27], v[26:27], v[224:225] op_sel_hi:[1, 0]
	v_pk_mul_f32 v[24:25], v[24:25], v[224:225] op_sel_hi:[1, 0]
	v_pk_mul_f32 v[22:23], v[22:23], v[224:225] op_sel_hi:[1, 0]
	v_pk_mul_f32 v[20:21], v[20:21], v[224:225] op_sel_hi:[1, 0]
	v_pk_mul_f32 v[18:19], v[18:19], v[224:225] op_sel_hi:[1, 0]
	v_pk_mul_f32 v[16:17], v[16:17], v[224:225] op_sel_hi:[1, 0]
	v_sub_f32_e32 v98, v98, v225
	v_sub_f32_e32 v99, v99, v225
	v_sub_f32_e32 v100, v100, v225
	v_sub_f32_e32 v101, v101, v225
	v_sub_f32_e32 v102, v102, v225
	v_sub_f32_e32 v103, v103, v225
	v_sub_f32_e32 v104, v104, v225
	v_sub_f32_e32 v105, v105, v225
	v_sub_f32_e32 v106, v106, v225
	v_sub_f32_e32 v107, v107, v225
	v_sub_f32_e32 v108, v108, v225
	v_sub_f32_e32 v109, v109, v225
	v_sub_f32_e32 v110, v110, v225
	v_sub_f32_e32 v111, v111, v225
	v_sub_f32_e32 v80, v80, v225
	v_sub_f32_e32 v81, v81, v225
	v_sub_f32_e32 v82, v82, v225
	v_sub_f32_e32 v83, v83, v225
	v_sub_f32_e32 v84, v84, v225
	v_sub_f32_e32 v85, v85, v225
	v_sub_f32_e32 v86, v86, v225
	v_sub_f32_e32 v87, v87, v225
	v_sub_f32_e32 v88, v88, v225
	v_sub_f32_e32 v89, v89, v225
	v_sub_f32_e32 v90, v90, v225
	v_sub_f32_e32 v91, v91, v225
	v_sub_f32_e32 v92, v92, v225
	v_sub_f32_e32 v93, v93, v225
	v_sub_f32_e32 v94, v94, v225
	v_sub_f32_e32 v95, v95, v225
; template <int DVT, bool FOX>
; DI void attn_step(const char* kb, const bf16x8 (&qf)[4], f32x16 (&o)[DVT], float& m, float& l, const bool diag, const int j, const int tq, const int r, const int hh) {
;     ...
;   f32x2 ls2 = {0.f, 0.f};
; #pragma unroll
;   for (int kt = 0; kt < 2; ++kt)
; #pragma unroll
;     for (int i = 0; i < 8; ++i) {
;       f32x2 pv = {__builtin_amdgcn_exp2f(st[kt][2 * i]), __builtin_amdgcn_exp2f(st[kt][2 * i + 1])};
;       st[kt][2 * i] = pv[0]; st[kt][2 * i + 1] = pv[1];
;       ls2 = ls2 + pv;
;     }
;   l += ls2[0] + ls2[1];
;   __builtin_amdgcn_sched_barrier(0);
;     ...
;   A_PVGROUP(0, va, vn); A_PVGROUP(1, vn, va); A_PVGROUP(2, va, vn); A_PVGROUP(3, vn, va);
.LBB0_663:
	v_exp_f32_e32 v96, v96
	v_exp_f32_e32 v97, v97
	v_exp_f32_e32 v98, v98
	v_exp_f32_e32 v99, v99
	v_pk_add_f32 v[224:225], v[96:97], 0 op_sel_hi:[1,0]
	v_exp_f32_e32 v100, v100
	v_exp_f32_e32 v101, v101
	v_pk_add_f32 v[224:225], v[98:99], v[224:225]
	v_exp_f32_e32 v102, v102
	v_exp_f32_e32 v103, v103
	v_pk_add_f32 v[224:225], v[100:101], v[224:225]
	v_exp_f32_e32 v104, v104
	v_exp_f32_e32 v105, v105
	v_pk_add_f32 v[224:225], v[102:103], v[224:225]
	v_exp_f32_e32 v106, v106
	v_exp_f32_e32 v107, v107
	v_pk_add_f32 v[224:225], v[104:105], v[224:225]
	v_exp_f32_e32 v108, v108
	v_exp_f32_e32 v109, v109
	v_pk_add_f32 v[224:225], v[106:107], v[224:225]
	v_exp_f32_e32 v110, v110
	v_exp_f32_e32 v111, v111
	v_pk_add_f32 v[224:225], v[108:109], v[224:225]
	v_exp_f32_e32 v80, v80
	v_exp_f32_e32 v81, v81
	v_pk_add_f32 v[224:225], v[110:111], v[224:225]
	v_exp_f32_e32 v82, v82
	v_exp_f32_e32 v83, v83
	v_pk_add_f32 v[224:225], v[80:81], v[224:225]
	v_exp_f32_e32 v84, v84
	v_exp_f32_e32 v85, v85
	v_pk_add_f32 v[224:225], v[82:83], v[224:225]
	v_exp_f32_e32 v86, v86
	v_exp_f32_e32 v87, v87
	v_pk_add_f32 v[224:225], v[84:85], v[224:225]
	v_exp_f32_e32 v88, v88
	v_exp_f32_e32 v89, v89
	v_pk_add_f32 v[224:225], v[86:87], v[224:225]
	v_exp_f32_e32 v90, v90
	v_exp_f32_e32 v91, v91
	v_pk_add_f32 v[224:225], v[88:89], v[224:225]
	v_exp_f32_e32 v92, v92
	v_exp_f32_e32 v93, v93
	v_pk_add_f32 v[224:225], v[90:91], v[224:225]
	v_exp_f32_e32 v94, v94
	v_exp_f32_e32 v95, v95
	v_pk_add_f32 v[224:225], v[92:93], v[224:225]
	s_nop 0
	v_pk_add_f32 v[224:225], v[94:95], v[224:225]
	v_cvt_pk_bf16_f32 v244, v96, v97
	v_cvt_pk_bf16_f32 v245, v98, v99
	v_cvt_pk_bf16_f32 v246, v100, v101
	v_cvt_pk_bf16_f32 v247, v102, v103
	v_cvt_pk_bf16_f32 v248, v104, v105
	v_cvt_pk_bf16_f32 v249, v106, v107
	v_cvt_pk_bf16_f32 v250, v108, v109
	v_cvt_pk_bf16_f32 v251, v110, v111
	v_cvt_pk_bf16_f32 v212, v80, v81
	v_cvt_pk_bf16_f32 v213, v82, v83
	v_cvt_pk_bf16_f32 v214, v84, v85
	v_cvt_pk_bf16_f32 v215, v86, v87
	v_cvt_pk_bf16_f32 v218, v88, v89
	v_cvt_pk_bf16_f32 v219, v90, v91
	v_cvt_pk_bf16_f32 v220, v92, v93
	v_cvt_pk_bf16_f32 v221, v94, v95
	v_add_f32_e32 v224, v224, v225
	s_nop 0
	v_add_f32_e32 v0, v0, v224
	ds_read_b128 v[80:83], v177 offset:9248
	ds_read_b128 v[84:87], v177 offset:13856
	ds_read_b128 v[88:91], v177 offset:18464
	ds_read_b128 v[92:95], v177 offset:23072
	s_waitcnt lgkmcnt(7)
	v_mfma_f32_32x32x16_bf16 v[64:79], v[152:155], v[244:247], v[64:79]
	s_waitcnt lgkmcnt(6)
	v_mfma_f32_32x32x16_bf16 v[48:63], v[10:13], v[244:247], v[48:63]
	s_waitcnt lgkmcnt(5)
	v_mfma_f32_32x32x16_bf16 v[32:47], v[6:9], v[244:247], v[32:47]
	s_waitcnt lgkmcnt(4)
	v_mfma_f32_32x32x16_bf16 v[16:31], v[2:5], v[244:247], v[16:31]
	ds_read_b128 v[2:5], v177 offset:9280
	ds_read_b128 v[6:9], v177 offset:13888
	ds_read_b128 v[10:13], v177 offset:18496
	ds_read_b128 v[96:99], v177 offset:23104
	s_waitcnt lgkmcnt(7)
	v_mfma_f32_32x32x16_bf16 v[64:79], v[80:83], v[248:251], v[64:79]
	s_waitcnt lgkmcnt(6)
	v_mfma_f32_32x32x16_bf16 v[48:63], v[84:87], v[248:251], v[48:63]
	s_waitcnt lgkmcnt(5)
	v_mfma_f32_32x32x16_bf16 v[32:47], v[88:91], v[248:251], v[32:47]
	s_waitcnt lgkmcnt(4)
	v_mfma_f32_32x32x16_bf16 v[16:31], v[92:95], v[248:251], v[16:31]
	ds_read_b128 v[80:83], v177 offset:9312
	ds_read_b128 v[84:87], v177 offset:13920
	ds_read_b128 v[88:91], v177 offset:18528
	ds_read_b128 v[92:95], v177 offset:23136
	s_waitcnt lgkmcnt(7)
	v_mfma_f32_32x32x16_bf16 v[64:79], v[2:5], v[212:215], v[64:79]
	s_waitcnt lgkmcnt(6)
	v_mfma_f32_32x32x16_bf16 v[48:63], v[6:9], v[212:215], v[48:63]
	s_waitcnt lgkmcnt(5)
	v_mfma_f32_32x32x16_bf16 v[32:47], v[10:13], v[212:215], v[32:47]
	s_waitcnt lgkmcnt(4)
	v_mfma_f32_32x32x16_bf16 v[16:31], v[96:99], v[212:215], v[16:31]
	s_waitcnt lgkmcnt(3)
	v_mfma_f32_32x32x16_bf16 v[64:79], v[80:83], v[218:221], v[64:79]
	s_waitcnt lgkmcnt(2)
	v_mfma_f32_32x32x16_bf16 v[48:63], v[84:87], v[218:221], v[48:63]
	s_waitcnt lgkmcnt(1)
	v_mfma_f32_32x32x16_bf16 v[32:47], v[88:91], v[218:221], v[32:47]
	s_waitcnt lgkmcnt(0)
	v_mfma_f32_32x32x16_bf16 v[16:31], v[92:95], v[218:221], v[16:31]

; #define MFMA32(a, b, c) __builtin_amdgcn_mfma_f32_32x32x16_bf16((a), (b), (c), 0, 0, 0)
; DI float xmax32(float v) { const u32x2 r_ = __builtin_amdgcn_permlane32_swap(__float_as_uint(v), __float_as_uint(v), false, false); return fmaxf(__uint_as_float(r_[0]), __uint_as_float(r_[1])); }
; template <int DVT, bool FOX>
; DI void attn_step(const char* kb, const bf16x8 (&qf)[4], f32x16 (&o)[DVT], float& m, float& l, const bool diag, const int j, const int tq, const int r, const int hh) {
;     ...
; #pragma unroll
;   for (int ks = 0; ks < 4; ++ks)
; #pragma unroll
;     for (int kt = 0; kt < 2; ++kt) st[kt] = MFMA32(kf[ks * 2 + kt], qf[ks], st[kt]);
;   bf16x8 va[DVT], vn[DVT];
; #pragma unroll
;   for (int d = 0; d < DVT; ++d) va[d] = *(const bf16x8*)(vb + (d * 32 + r) * LROW + (8 * hh) * 2);
;   __builtin_amdgcn_sched_barrier(0);
;   {
;     const f32x2 mm = {m, m};
; #pragma unroll
;     for (int kt = 0; kt < 2; ++kt)
; #pragma unroll
;       for (int i = 0; i < 8; ++i) { f32x2 z = {st[kt][2 * i], st[kt][2 * i + 1]}; z = z - mm; st[kt][2 * i] = z[0]; st[kt][2 * i + 1] = z[1]; }
;   }
;   if (FOX) {
;     if (diag) {
; #pragma unroll
;       for (int kt = 0; kt < 2; ++kt)
; #pragma unroll
;         for (int i = 0; i < 16; ++i) {
;           const int key = j * 64 + kt * 32 + (i & 3) + 8 * (i >> 2) + 4 * hh;
;           if (key > tq) st[kt][i] = -INFINITY;
;         }
;     }
;   }
;   float mx;
;   {
;     float a0 = fmaxf(fmaxf(st[0][0], st[0][1]), st[0][2]), a1 = fmaxf(fmaxf(st[1][0], st[1][1]), st[1][2]);
; #pragma unroll
;     for (int i = 3; i < 15; i += 2) { a0 = fmaxf(fmaxf(a0, st[0][i]), st[0][i + 1]); a1 = fmaxf(fmaxf(a1, st[1][i]), st[1][i + 1]); }
;     mx = fmaxf(fmaxf(a0, a1), fmaxf(st[0][15], st[1][15]));
;   }
;   mx = xmax32(mx);
;   if (__any(diag || mx > 8.f)) {
;     const float d = (diag || mx > 0.f) ? mx : 0.f;
;     const float alpha = diag ? 0.f : __builtin_amdgcn_exp2f(-d);
;     m += d;
;     l *= alpha;
; #pragma unroll
;     for (int dd = 0; dd < DVT; ++dd)
; #pragma unroll
;       for (int i = 0; i < 16; ++i) o[dd][i] *= alpha;
;     const f32x2 d2 = {d, d};
; #pragma unroll
;     for (int kt = 0; kt < 2; ++kt)
; #pragma unroll
;       for (int i = 0; i < 8; ++i) { f32x2 z = {st[kt][2 * i], st[kt][2 * i + 1]}; z = z - d2; st[kt][2 * i] = z[0]; st[kt][2 * i + 1] = z[1]; }
;   }
.LBB0_668:
	ds_read_b128 v[2:5], v177 offset:27904
	ds_read_b128 v[6:9], v177 offset:27936
	ds_read_b128 v[10:13], v177 offset:32512
	ds_read_b128 v[152:155], v177 offset:32544
	ds_read_b128 v[168:171], v177 offset:27968
	ds_read_b128 v[172:175], v177 offset:28000
	ds_read_b128 v[184:187], v177 offset:32576
	ds_read_b128 v[188:191], v177 offset:32608
	s_cmp_eq_u32 s3, 0
	s_cselect_b64 s[4:5], -1, 0
	s_waitcnt lgkmcnt(7)
	v_mfma_f32_32x32x16_bf16 v[96:111], v[2:5], v[112:115], v[228:243]
	s_waitcnt lgkmcnt(5)
	v_mfma_f32_32x32x16_bf16 v[80:95], v[10:13], v[112:115], v[228:243]
	v_mfma_f32_32x32x16_bf16 v[96:111], v[6:9], v[116:119], v[96:111]
	s_waitcnt lgkmcnt(4)
	v_mfma_f32_32x32x16_bf16 v[80:95], v[152:155], v[116:119], v[80:95]
	ds_read_b128 v[152:155], v177 offset:37120
	ds_read_b128 v[10:13], v177 offset:41728
	ds_read_b128 v[6:9], v177 offset:46336
	ds_read_b128 v[2:5], v177 offset:50944
	s_waitcnt lgkmcnt(7)
	v_mfma_f32_32x32x16_bf16 v[96:111], v[168:171], v[120:123], v[96:111]
	s_waitcnt lgkmcnt(5)
	v_mfma_f32_32x32x16_bf16 v[80:95], v[184:187], v[120:123], v[80:95]
	v_mfma_f32_32x32x16_bf16 v[96:111], v[172:175], v[124:127], v[96:111]
	s_waitcnt lgkmcnt(4)
	v_mfma_f32_32x32x16_bf16 v[80:95], v[188:191], v[124:127], v[80:95]
	s_nop 10
	v_max3_f32 v224, v96, v97, v98
	v_max3_f32 v225, v80, v81, v82
	v_max3_f32 v224, v224, v99, v100
	v_max3_f32 v225, v225, v83, v84
	v_max3_f32 v224, v224, v101, v102
	v_max3_f32 v225, v225, v85, v86
	v_max3_f32 v224, v224, v103, v104
	v_max3_f32 v225, v225, v87, v88
	v_max3_f32 v224, v224, v105, v106
	v_max3_f32 v225, v225, v89, v90
	v_max3_f32 v224, v224, v107, v108
	v_max3_f32 v225, v225, v91, v92
	v_max3_f32 v224, v224, v109, v110
	v_max3_f32 v225, v225, v93, v94
	v_max_f32_e32 v226, v111, v95
	v_max3_f32 v224, v224, v225, v226
	v_mov_b32_e32 v225, v224
	s_nop 1
	v_permlane32_swap_b32_e32 v224, v225
	v_max_f32_e32 v224, v224, v225
	v_cmp_lt_f32_e32 vcc, s92, v224
	s_or_b64 vcc, s[4:5], vcc
	s_cbranch_vccz .LBB0_670
	v_cmp_lt_f32_e32 vcc, 0, v224
	s_or_b64 vcc, s[4:5], vcc
	s_nop 0
	v_cndmask_b32_e32 v225, 0, v224, vcc
	v_exp_f32_e64 v224, -v225
	v_add_f32_e32 v166, v166, v225
	v_sub_f32_e32 v228, v228, v225
	v_sub_f32_e32 v229, v229, v225
	v_sub_f32_e32 v230, v230, v225
	v_sub_f32_e32 v231, v231, v225
	v_sub_f32_e32 v232, v232, v225
	v_sub_f32_e32 v233, v233, v225
	v_sub_f32_e32 v234, v234, v225
	v_sub_f32_e32 v235, v235, v225
	v_sub_f32_e32 v236, v236, v225
	v_sub_f32_e32 v237, v237, v225
	v_sub_f32_e32 v238, v238, v225
	v_sub_f32_e32 v239, v239, v225
	v_sub_f32_e32 v240, v240, v225
	v_sub_f32_e32 v241, v241, v225
	v_sub_f32_e32 v242, v242, v225
	v_sub_f32_e32 v243, v243, v225
	v_sub_f32_e32 v96, v96, v225
	v_sub_f32_e32 v97, v97, v225
	v_cndmask_b32_e64 v224, v224, 0, s[4:5]
	v_mul_f32_e32 v0, v0, v224
	v_pk_mul_f32 v[78:79], v[78:79], v[224:225] op_sel_hi:[1, 0]
	v_pk_mul_f32 v[76:77], v[76:77], v[224:225] op_sel_hi:[1, 0]
	v_pk_mul_f32 v[74:75], v[74:75], v[224:225] op_sel_hi:[1, 0]
	v_pk_mul_f32 v[72:73], v[72:73], v[224:225] op_sel_hi:[1, 0]
	v_pk_mul_f32 v[70:71], v[70:71], v[224:225] op_sel_hi:[1, 0]
	v_pk_mul_f32 v[68:69], v[68:69], v[224:225] op_sel_hi:[1, 0]
	v_pk_mul_f32 v[66:67], v[66:67], v[224:225] op_sel_hi:[1, 0]
	v_pk_mul_f32 v[64:65], v[64:65], v[224:225] op_sel_hi:[1, 0]
	v_pk_mul_f32 v[62:63], v[62:63], v[224:225] op_sel_hi:[1, 0]
	v_pk_mul_f32 v[60:61], v[60:61], v[224:225] op_sel_hi:[1, 0]
	v_pk_mul_f32 v[58:59], v[58:59], v[224:225] op_sel_hi:[1, 0]
	v_pk_mul_f32 v[56:57], v[56:57], v[224:225] op_sel_hi:[1, 0]
	v_pk_mul_f32 v[54:55], v[54:55], v[224:225] op_sel_hi:[1, 0]
	v_pk_mul_f32 v[52:53], v[52:53], v[224:225] op_sel_hi:[1, 0]
	v_pk_mul_f32 v[50:51], v[50:51], v[224:225] op_sel_hi:[1, 0]
	v_pk_mul_f32 v[48:49], v[48:49], v[224:225] op_sel_hi:[1, 0]
	v_pk_mul_f32 v[46:47], v[46:47], v[224:225] op_sel_hi:[1, 0]
	v_pk_mul_f32 v[44:45], v[44:45], v[224:225] op_sel_hi:[1, 0]
	v_pk_mul_f32 v[42:43], v[42:43], v[224:225] op_sel_hi:[1, 0]
	v_pk_mul_f32 v[40:41], v[40:41], v[224:225] op_sel_hi:[1, 0]
	v_pk_mul_f32 v[38:39], v[38:39], v[224:225] op_sel_hi:[1, 0]
	v_pk_mul_f32 v[36:37], v[36:37], v[224:225] op_sel_hi:[1, 0]
	v_pk_mul_f32 v[34:35], v[34:35], v[224:225] op_sel_hi:[1, 0]
	v_pk_mul_f32 v[32:33], v[32:33], v[224:225] op_sel_hi:[1, 0]
	v_pk_mul_f32 v[30:31], v[30:31], v[224:225] op_sel_hi:[1, 0]
	v_pk_mul_f32 v[28:29], v[28:29], v[224:225] op_sel_hi:[1, 0]
	v_pk_mul_f32 v[26:27], v[26:27], v[224:225] op_sel_hi:[1, 0]
	v_pk_mul_f32 v[24:25], v[24:25], v[224:225] op_sel_hi:[1, 0]
	v_pk_mul_f32 v[22:23], v[22:23], v[224:225] op_sel_hi:[1, 0]
	v_pk_mul_f32 v[20:21], v[20:21], v[224:225] op_sel_hi:[1, 0]
	v_pk_mul_f32 v[18:19], v[18:19], v[224:225] op_sel_hi:[1, 0]
	v_pk_mul_f32 v[16:17], v[16:17], v[224:225] op_sel_hi:[1, 0]
	v_sub_f32_e32 v98, v98, v225
	v_sub_f32_e32 v99, v99, v225
	v_sub_f32_e32 v100, v100, v225
	v_sub_f32_e32 v101, v101, v225
	v_sub_f32_e32 v102, v102, v225
	v_sub_f32_e32 v103, v103, v225
	v_sub_f32_e32 v104, v104, v225
	v_sub_f32_e32 v105, v105, v225
	v_sub_f32_e32 v106, v106, v225
	v_sub_f32_e32 v107, v107, v225
	v_sub_f32_e32 v108, v108, v225
	v_sub_f32_e32 v109, v109, v225
	v_sub_f32_e32 v110, v110, v225
	v_sub_f32_e32 v111, v111, v225
	v_sub_f32_e32 v80, v80, v225
	v_sub_f32_e32 v81, v81, v225
	v_sub_f32_e32 v82, v82, v225
	v_sub_f32_e32 v83, v83, v225
	v_sub_f32_e32 v84, v84, v225
	v_sub_f32_e32 v85, v85, v225
	v_sub_f32_e32 v86, v86, v225
	v_sub_f32_e32 v87, v87, v225
	v_sub_f32_e32 v88, v88, v225
	v_sub_f32_e32 v89, v89, v225
	v_sub_f32_e32 v90, v90, v225
	v_sub_f32_e32 v91, v91, v225
	v_sub_f32_e32 v92, v92, v225
	v_sub_f32_e32 v93, v93, v225
	v_sub_f32_e32 v94, v94, v225
	v_sub_f32_e32 v95, v95, v225
; template <int DVT, bool FOX>
; DI void attn_step(const char* kb, const bf16x8 (&qf)[4], f32x16 (&o)[DVT], float& m, float& l, const bool diag, const int j, const int tq, const int r, const int hh) {
;     ...
;   f32x2 ls2 = {0.f, 0.f};
; #pragma unroll
;   for (int kt = 0; kt < 2; ++kt)
; #pragma unroll
;     for (int i = 0; i < 8; ++i) {
;       f32x2 pv = {__builtin_amdgcn_exp2f(st[kt][2 * i]), __builtin_amdgcn_exp2f(st[kt][2 * i + 1])};
;       st[kt][2 * i] = pv[0]; st[kt][2 * i + 1] = pv[1];
;       ls2 = ls2 + pv;
;     }
;   l += ls2[0] + ls2[1];
;   __builtin_amdgcn_sched_barrier(0);
;     ...
;   A_PVGROUP(0, va, vn); A_PVGROUP(1, vn, va); A_PVGROUP(2, va, vn); A_PVGROUP(3, vn, va);
.LBB0_670:
	v_exp_f32_e32 v96, v96
	v_exp_f32_e32 v97, v97
	v_exp_f32_e32 v98, v98
	v_exp_f32_e32 v99, v99
	v_pk_add_f32 v[224:225], v[96:97], 0 op_sel_hi:[1,0]
	v_exp_f32_e32 v100, v100
	v_exp_f32_e32 v101, v101
	v_pk_add_f32 v[224:225], v[98:99], v[224:225]
	v_exp_f32_e32 v102, v102
	v_exp_f32_e32 v103, v103
	v_pk_add_f32 v[224:225], v[100:101], v[224:225]
	v_exp_f32_e32 v104, v104
	v_exp_f32_e32 v105, v105
	v_pk_add_f32 v[224:225], v[102:103], v[224:225]
	v_exp_f32_e32 v106, v106
	v_exp_f32_e32 v107, v107
	v_pk_add_f32 v[224:225], v[104:105], v[224:225]
	v_exp_f32_e32 v108, v108
	v_exp_f32_e32 v109, v109
	v_pk_add_f32 v[224:225], v[106:107], v[224:225]
	v_exp_f32_e32 v110, v110
	v_exp_f32_e32 v111, v111
	v_pk_add_f32 v[224:225], v[108:109], v[224:225]
	v_exp_f32_e32 v80, v80
	v_exp_f32_e32 v81, v81
	v_pk_add_f32 v[224:225], v[110:111], v[224:225]
	v_exp_f32_e32 v82, v82
	v_exp_f32_e32 v83, v83
	v_pk_add_f32 v[224:225], v[80:81], v[224:225]
	v_exp_f32_e32 v84, v84
	v_exp_f32_e32 v85, v85
	v_pk_add_f32 v[224:225], v[82:83], v[224:225]
	v_exp_f32_e32 v86, v86
	v_exp_f32_e32 v87, v87
	v_pk_add_f32 v[224:225], v[84:85], v[224:225]
	v_exp_f32_e32 v88, v88
	v_exp_f32_e32 v89, v89
	v_pk_add_f32 v[224:225], v[86:87], v[224:225]
	v_exp_f32_e32 v90, v90
	v_exp_f32_e32 v91, v91
	v_pk_add_f32 v[224:225], v[88:89], v[224:225]
	v_exp_f32_e32 v92, v92
	v_exp_f32_e32 v93, v93
	v_pk_add_f32 v[224:225], v[90:91], v[224:225]
	v_exp_f32_e32 v94, v94
	v_exp_f32_e32 v95, v95
	v_pk_add_f32 v[224:225], v[92:93], v[224:225]
	s_nop 0
	v_pk_add_f32 v[224:225], v[94:95], v[224:225]
	v_cvt_pk_bf16_f32 v244, v96, v97
	v_cvt_pk_bf16_f32 v245, v98, v99
	v_cvt_pk_bf16_f32 v246, v100, v101
	v_cvt_pk_bf16_f32 v247, v102, v103
	v_cvt_pk_bf16_f32 v248, v104, v105
	v_cvt_pk_bf16_f32 v249, v106, v107
	v_cvt_pk_bf16_f32 v250, v108, v109
	v_cvt_pk_bf16_f32 v251, v110, v111
	v_cvt_pk_bf16_f32 v212, v80, v81
	v_cvt_pk_bf16_f32 v213, v82, v83
	v_cvt_pk_bf16_f32 v214, v84, v85
	v_cvt_pk_bf16_f32 v215, v86, v87
	v_cvt_pk_bf16_f32 v218, v88, v89
	v_cvt_pk_bf16_f32 v219, v90, v91
	v_cvt_pk_bf16_f32 v220, v92, v93
	v_cvt_pk_bf16_f32 v221, v94, v95
	v_add_f32_e32 v224, v224, v225
	s_nop 0
	v_add_f32_e32 v0, v0, v224
	ds_read_b128 v[80:83], v177 offset:37152
	ds_read_b128 v[84:87], v177 offset:41760
	ds_read_b128 v[88:91], v177 offset:46368
	ds_read_b128 v[92:95], v177 offset:50976
	s_waitcnt lgkmcnt(7)
	v_mfma_f32_32x32x16_bf16 v[64:79], v[152:155], v[244:247], v[64:79]
	s_waitcnt lgkmcnt(6)
	v_mfma_f32_32x32x16_bf16 v[48:63], v[10:13], v[244:247], v[48:63]
	s_waitcnt lgkmcnt(5)
	v_mfma_f32_32x32x16_bf16 v[32:47], v[6:9], v[244:247], v[32:47]
	s_waitcnt lgkmcnt(4)
	v_mfma_f32_32x32x16_bf16 v[16:31], v[2:5], v[244:247], v[16:31]
	ds_read_b128 v[2:5], v177 offset:37184
	ds_read_b128 v[6:9], v177 offset:41792
	ds_read_b128 v[10:13], v177 offset:46400
	ds_read_b128 v[96:99], v177 offset:51008
	s_waitcnt lgkmcnt(7)
	v_mfma_f32_32x32x16_bf16 v[64:79], v[80:83], v[248:251], v[64:79]
	s_waitcnt lgkmcnt(6)
	v_mfma_f32_32x32x16_bf16 v[48:63], v[84:87], v[248:251], v[48:63]
	s_waitcnt lgkmcnt(5)
	v_mfma_f32_32x32x16_bf16 v[32:47], v[88:91], v[248:251], v[32:47]
	s_waitcnt lgkmcnt(4)
	v_mfma_f32_32x32x16_bf16 v[16:31], v[92:95], v[248:251], v[16:31]
	ds_read_b128 v[80:83], v177 offset:37216
	ds_read_b128 v[84:87], v177 offset:41824
	ds_read_b128 v[88:91], v177 offset:46432
	ds_read_b128 v[92:95], v177 offset:51040
	s_waitcnt lgkmcnt(7)
	v_mfma_f32_32x32x16_bf16 v[64:79], v[2:5], v[212:215], v[64:79]
	s_waitcnt lgkmcnt(6)
	v_mfma_f32_32x32x16_bf16 v[48:63], v[6:9], v[212:215], v[48:63]
	s_waitcnt lgkmcnt(5)
	v_mfma_f32_32x32x16_bf16 v[32:47], v[10:13], v[212:215], v[32:47]
	s_waitcnt lgkmcnt(4)
	v_mfma_f32_32x32x16_bf16 v[16:31], v[96:99], v[212:215], v[16:31]
	s_waitcnt lgkmcnt(3)
	v_mfma_f32_32x32x16_bf16 v[64:79], v[80:83], v[218:221], v[64:79]
	s_waitcnt lgkmcnt(2)
	v_mfma_f32_32x32x16_bf16 v[48:63], v[84:87], v[218:221], v[48:63]
	s_waitcnt lgkmcnt(1)
	v_mfma_f32_32x32x16_bf16 v[32:47], v[88:91], v[218:221], v[32:47]
	s_waitcnt lgkmcnt(0)
	v_mfma_f32_32x32x16_bf16 v[16:31], v[92:95], v[218:221], v[16:31]
	s_cmp_eq_u32 s27, 0
	s_cbranch_scc0 .LBB0_657
